# GEMM accumulator zeroing with v_mov_b64 pairs instead of 128 v_mov_b32
# speedup vs baseline: 1.0027x; 1.0027x over previous
.LBB0_169:
	s_ashr_i32 s15, s14, 31
	s_lshl_b64 s[16:17], s[14:15], 19
	s_add_u32 s16, s80, s16
	s_addc_u32 s17, s81, s17
	s_and_b64 s[18:19], s[2:3], exec
	s_cselect_b32 s15, s17, s31
	s_cselect_b32 s69, s16, s30
	s_ashr_i32 s13, s12, 31
	s_lshl_b64 s[18:19], s[12:13], 19
	s_add_u32 s18, s22, s18
	s_addc_u32 s19, s23, s19
	s_and_b64 s[52:53], s[2:3], exec
	s_cselect_b32 s13, s19, s29
	s_cselect_b32 s70, s18, s28
	s_add_u32 s52, s30, 0x40080
	s_addc_u32 s53, s31, 0
	s_add_u32 s71, s28, 0x100
	v_mov_b32_e32 v2, 0
	v_mov_b32_e32 v3, 0
	v_mov_b64_e32 v[4:5], v[2:3]
	v_mov_b64_e32 v[6:7], v[2:3]
	v_mov_b64_e32 v[8:9], v[2:3]
	v_mov_b64_e32 v[10:11], v[2:3]
	v_mov_b64_e32 v[12:13], v[2:3]
	v_mov_b64_e32 v[14:15], v[2:3]
	v_mov_b64_e32 v[16:17], v[2:3]
	v_mov_b64_e32 v[18:19], v[2:3]
	v_mov_b64_e32 v[20:21], v[2:3]
	v_mov_b64_e32 v[22:23], v[2:3]
	v_mov_b64_e32 v[24:25], v[2:3]
	v_mov_b64_e32 v[26:27], v[2:3]
	v_mov_b64_e32 v[28:29], v[2:3]
	v_mov_b64_e32 v[30:31], v[2:3]
	v_mov_b64_e32 v[32:33], v[2:3]
	v_mov_b64_e32 v[34:35], v[2:3]
	v_mov_b64_e32 v[36:37], v[2:3]
	v_mov_b64_e32 v[38:39], v[2:3]
	v_mov_b64_e32 v[40:41], v[2:3]
	v_mov_b64_e32 v[42:43], v[2:3]
	v_mov_b64_e32 v[44:45], v[2:3]
	v_mov_b64_e32 v[46:47], v[2:3]
	v_mov_b64_e32 v[48:49], v[2:3]
	v_mov_b64_e32 v[50:51], v[2:3]
	v_mov_b64_e32 v[52:53], v[2:3]
	v_mov_b64_e32 v[54:55], v[2:3]
	v_mov_b64_e32 v[56:57], v[2:3]
	v_mov_b64_e32 v[58:59], v[2:3]
	v_mov_b64_e32 v[60:61], v[2:3]
	v_mov_b64_e32 v[62:63], v[2:3]
	v_mov_b64_e32 v[64:65], v[2:3]
	v_mov_b64_e32 v[66:67], v[2:3]
	v_mov_b64_e32 v[68:69], v[2:3]
	v_mov_b64_e32 v[70:71], v[2:3]
	v_mov_b64_e32 v[72:73], v[2:3]
	v_mov_b64_e32 v[74:75], v[2:3]
	v_mov_b64_e32 v[76:77], v[2:3]
	v_mov_b64_e32 v[78:79], v[2:3]
	v_mov_b64_e32 v[80:81], v[2:3]
	v_mov_b64_e32 v[82:83], v[2:3]
	v_mov_b64_e32 v[84:85], v[2:3]
	v_mov_b64_e32 v[86:87], v[2:3]
	v_mov_b64_e32 v[88:89], v[2:3]
	v_mov_b64_e32 v[90:91], v[2:3]
	v_mov_b64_e32 v[92:93], v[2:3]
	v_mov_b64_e32 v[94:95], v[2:3]
	v_mov_b64_e32 v[96:97], v[2:3]
	v_mov_b64_e32 v[98:99], v[2:3]
	v_mov_b64_e32 v[100:101], v[2:3]
	v_mov_b64_e32 v[102:103], v[2:3]
	v_mov_b64_e32 v[104:105], v[2:3]
	v_mov_b64_e32 v[106:107], v[2:3]
	v_mov_b64_e32 v[108:109], v[2:3]
	v_mov_b64_e32 v[110:111], v[2:3]
	v_mov_b64_e32 v[112:113], v[2:3]
	v_mov_b64_e32 v[114:115], v[2:3]
	v_mov_b64_e32 v[116:117], v[2:3]
	v_mov_b64_e32 v[118:119], v[2:3]
	v_mov_b64_e32 v[120:121], v[2:3]
	v_mov_b64_e32 v[122:123], v[2:3]
	v_mov_b64_e32 v[124:125], v[2:3]
	v_mov_b64_e32 v[126:127], v[2:3]
	v_mov_b64_e32 v[128:129], v[2:3]
	s_addc_u32 s72, s29, 0
	s_mov_b32 s73, -2
	s_waitcnt lgkmcnt(0)

.LBB0_718:
	v_and_b32_e32 v1, 15, v0
	v_and_b32_e32 v14, 48, v0
	v_lshlrev_b32_e32 v16, 2, v0
	s_sext_i32_i8 s8, s0
	v_lshl_or_b32 v15, v1, 6, v14
	s_lshl_b32 s0, s22, 13
	v_and_b32_e32 v16, 32, v16
	s_mov_b64 s[12:13], 0x80
	s_and_b32 s23, s9, 3
	v_bitop3_b32 v15, v15, s0, v16 bitop3:0xde
	v_lshlrev_b32_e32 v17, 6, v0
	s_movk_i32 s0, 0x3c0
	s_add_i32 m0, s51, 0x18000
	v_lshl_add_u64 v[8:9], v[8:9], 0, s[12:13]
	v_and_or_b32 v14, v17, s0, v14
	s_lshl_b32 s0, s23, 12
	s_waitcnt vmcnt(2)
	s_barrier
	global_load_lds_dwordx4 v[8:9], off
	v_lshl_add_u64 v[6:7], v[6:7], 0, s[12:13]
	s_add_i32 m0, s51, 0x1a000
	s_add_i32 s56, s51, 0x8000
	s_add_i32 s57, s51, 0xa000
	global_load_lds_dwordx4 v[6:7], off
	v_lshl_add_u64 v[4:5], v[4:5], 0, s[12:13]
	s_mov_b32 m0, s56
	s_add_u32 s2, s18, 0xb0080
	global_load_lds_dwordx4 v[4:5], off
	v_lshl_add_u64 v[2:3], v[2:3], 0, s[12:13]
	s_mov_b32 m0, s57
	s_addc_u32 s3, s19, 0
	global_load_lds_dwordx4 v[2:3], off
	s_add_i32 m0, s51, 0x1c000
	v_lshl_add_u64 v[2:3], s[2:3], 0, v[132:133]
	global_load_lds_dwordx4 v[2:3], off
	v_lshl_add_u64 v[2:3], s[2:3], 0, v[136:137]
	s_add_i32 m0, s51, 0x1e000
	v_bitop3_b32 v153, s0, v14, v16 bitop3:0xf6
	global_load_lds_dwordx4 v[2:3], off
	v_add_u16_e32 v2, v10, v11
	v_lshrrev_b16_e32 v4, 1, v2
	s_mov_b64 s[0:1], 0xb0080
	s_waitcnt vmcnt(6)
	v_add_lshl_u32 v2, v12, v4, 1
	v_mov_b32_e32 v3, v133
	v_lshl_add_u64 v[140:141], v[2:3], 0, s[0:1]
	v_add_lshl_u32 v2, v13, v4, 1
	v_lshl_or_b32 v152, s22, 6, v1
	v_lshl_add_u64 v[142:143], v[2:3], 0, s[0:1]
	v_mov_b64_e32 v[144:145], 0x100
	v_mov_b64_e32 v[146:147], 0xff
	s_add_i32 s58, 0, 0x10000
	s_add_i32 s59, 0, 0x14000
	v_add_u32_e32 v154, 0, v15
	v_mov_b32_e32 v4, v133
	v_mov_b32_e32 v5, v133
	v_mov_b64_e32 v[6:7], v[4:5]
	v_mov_b64_e32 v[8:9], v[4:5]
	v_mov_b64_e32 v[10:11], v[4:5]
	v_mov_b64_e32 v[12:13], v[4:5]
	v_mov_b64_e32 v[14:15], v[4:5]
	v_mov_b64_e32 v[16:17], v[4:5]
	v_mov_b64_e32 v[18:19], v[4:5]
	v_mov_b64_e32 v[20:21], v[4:5]
	v_mov_b64_e32 v[22:23], v[4:5]
	v_mov_b64_e32 v[24:25], v[4:5]
	v_mov_b64_e32 v[26:27], v[4:5]
	v_mov_b64_e32 v[28:29], v[4:5]
	v_mov_b64_e32 v[30:31], v[4:5]
	v_mov_b64_e32 v[32:33], v[4:5]
	v_mov_b64_e32 v[34:35], v[4:5]
	v_mov_b64_e32 v[36:37], v[4:5]
	v_mov_b64_e32 v[38:39], v[4:5]
	v_mov_b64_e32 v[40:41], v[4:5]
	v_mov_b64_e32 v[42:43], v[4:5]
	v_mov_b64_e32 v[44:45], v[4:5]
	v_mov_b64_e32 v[46:47], v[4:5]
	v_mov_b64_e32 v[48:49], v[4:5]
	v_mov_b64_e32 v[50:51], v[4:5]
	v_mov_b64_e32 v[52:53], v[4:5]
	v_mov_b64_e32 v[54:55], v[4:5]
	v_mov_b64_e32 v[56:57], v[4:5]
	v_mov_b64_e32 v[58:59], v[4:5]
	v_mov_b64_e32 v[60:61], v[4:5]
	v_mov_b64_e32 v[62:63], v[4:5]
	v_mov_b64_e32 v[64:65], v[4:5]
	v_mov_b64_e32 v[66:67], v[4:5]
	v_mov_b64_e32 v[68:69], v[4:5]
	v_mov_b64_e32 v[70:71], v[4:5]
	v_mov_b64_e32 v[72:73], v[4:5]
	v_mov_b64_e32 v[74:75], v[4:5]
	v_mov_b64_e32 v[76:77], v[4:5]
	v_mov_b64_e32 v[78:79], v[4:5]
	v_mov_b64_e32 v[80:81], v[4:5]
	v_mov_b64_e32 v[82:83], v[4:5]
	v_mov_b64_e32 v[84:85], v[4:5]
	v_mov_b64_e32 v[86:87], v[4:5]
	v_mov_b64_e32 v[88:89], v[4:5]
	v_mov_b64_e32 v[90:91], v[4:5]
	v_mov_b64_e32 v[92:93], v[4:5]
	v_mov_b64_e32 v[94:95], v[4:5]
	v_mov_b64_e32 v[96:97], v[4:5]
	v_mov_b64_e32 v[98:99], v[4:5]
	v_mov_b64_e32 v[100:101], v[4:5]
	v_mov_b64_e32 v[102:103], v[4:5]
	v_mov_b64_e32 v[104:105], v[4:5]
	v_mov_b64_e32 v[106:107], v[4:5]
	v_mov_b64_e32 v[108:109], v[4:5]
	v_mov_b64_e32 v[110:111], v[4:5]
	v_mov_b64_e32 v[112:113], v[4:5]
	v_mov_b64_e32 v[114:115], v[4:5]
	v_mov_b64_e32 v[116:117], v[4:5]
	v_mov_b64_e32 v[118:119], v[4:5]
	v_mov_b64_e32 v[120:121], v[4:5]
	v_mov_b64_e32 v[122:123], v[4:5]
	v_mov_b64_e32 v[124:125], v[4:5]
	v_mov_b64_e32 v[126:127], v[4:5]
	v_mov_b64_e32 v[128:129], v[4:5]
	v_mov_b32_e32 v2, v4
	s_waitcnt lgkmcnt(0)
	s_barrier

.LBB0_730:
	v_add_u32_e32 v155, s58, v153
	ds_read_b128 v[156:159], v155
	ds_read_b128 v[160:163], v155 offset:1024
	ds_read_b128 v[164:167], v155 offset:2048
	ds_read_b128 v[168:171], v155 offset:3072
	v_add_u32_e32 v155, s59, v153
	s_add_u32 s20, s10, s18
	ds_read_b128 v[172:175], v155
	ds_read_b128 v[176:179], v155 offset:1024
	ds_read_b128 v[180:183], v155 offset:2048
	ds_read_b128 v[184:187], v155 offset:3072
	s_addc_u32 s21, s11, s19
	s_add_u32 s20, s20, 0x100
	s_addc_u32 s21, s21, 0
	s_add_u32 s64, s15, s18
	s_addc_u32 s65, s62, s19
	s_cmpk_eq_i32 s18, 0x1500
	s_cselect_b32 s29, s17, s21
	s_cselect_b32 s28, s16, s20
	s_cselect_b32 s21, s1, s65
	s_cselect_b32 s20, s0, s64
	v_lshl_add_u64 v[220:221], v[148:149], 0, s[18:19]
	s_add_i32 m0, s51, 0xc000
	ds_read_b128 v[188:191], v154
	ds_read_b128 v[192:195], v154 offset:1024
	ds_read_b128 v[196:199], v154 offset:2048
	ds_read_b128 v[200:203], v154 offset:3072
	ds_read_b128 v[204:207], v154 offset:4096
	ds_read_b128 v[208:211], v154 offset:5120
	ds_read_b128 v[212:215], v154 offset:6144
	ds_read_b128 v[216:219], v154 offset:7168
	global_load_lds_dwordx4 v[220:221], off
	v_lshl_add_u64 v[220:221], v[150:151], 0, s[18:19]
	s_add_i32 m0, s51, 0xe000
	s_nop 0
	global_load_lds_dwordx4 v[220:221], off
	s_waitcnt vmcnt(8)
	s_waitcnt lgkmcnt(0)
	s_barrier
	s_setprio 1
	s_waitcnt lgkmcnt(0)
	v_mfma_f32_16x16x32_bf16 v[126:129], v[156:159], v[188:191], v[126:129]
	v_mfma_f32_16x16x32_bf16 v[122:125], v[164:167], v[188:191], v[122:125]
	v_mfma_f32_16x16x32_bf16 v[110:113], v[156:159], v[196:199], v[110:113]
	v_mfma_f32_16x16x32_bf16 v[106:109], v[164:167], v[196:199], v[106:109]
	v_mfma_f32_16x16x32_bf16 v[94:97], v[156:159], v[204:207], v[94:97]
	v_mfma_f32_16x16x32_bf16 v[90:93], v[164:167], v[204:207], v[90:93]
	v_mfma_f32_16x16x32_bf16 v[78:81], v[156:159], v[212:215], v[78:81]
	v_mfma_f32_16x16x32_bf16 v[74:77], v[164:167], v[212:215], v[74:77]
	v_mfma_f32_16x16x32_bf16 v[126:129], v[160:163], v[192:195], v[126:129]
	v_mfma_f32_16x16x32_bf16 v[122:125], v[168:171], v[192:195], v[122:125]
	v_mfma_f32_16x16x32_bf16 v[110:113], v[160:163], v[200:203], v[110:113]
	v_mfma_f32_16x16x32_bf16 v[106:109], v[168:171], v[200:203], v[106:109]
	v_mfma_f32_16x16x32_bf16 v[94:97], v[160:163], v[208:211], v[94:97]
	v_mfma_f32_16x16x32_bf16 v[90:93], v[168:171], v[208:211], v[90:93]
	v_mfma_f32_16x16x32_bf16 v[78:81], v[160:163], v[216:219], v[78:81]
	v_mfma_f32_16x16x32_bf16 v[74:77], v[168:171], v[216:219], v[74:77]
	s_setprio 0
	s_setprio 1
	v_mfma_f32_16x16x32_bf16 v[118:121], v[172:175], v[188:191], v[118:121]
	v_mfma_f32_16x16x32_bf16 v[114:117], v[180:183], v[188:191], v[114:117]
	v_mfma_f32_16x16x32_bf16 v[102:105], v[172:175], v[196:199], v[102:105]
	v_mfma_f32_16x16x32_bf16 v[98:101], v[180:183], v[196:199], v[98:101]
	v_mfma_f32_16x16x32_bf16 v[86:89], v[172:175], v[204:207], v[86:89]
	v_mfma_f32_16x16x32_bf16 v[82:85], v[180:183], v[204:207], v[82:85]
	v_mfma_f32_16x16x32_bf16 v[70:73], v[172:175], v[212:215], v[70:73]
	v_mfma_f32_16x16x32_bf16 v[66:69], v[180:183], v[212:215], v[66:69]
	v_mfma_f32_16x16x32_bf16 v[118:121], v[176:179], v[192:195], v[118:121]
	v_mfma_f32_16x16x32_bf16 v[114:117], v[184:187], v[192:195], v[114:117]
	v_mfma_f32_16x16x32_bf16 v[102:105], v[176:179], v[200:203], v[102:105]
	v_mfma_f32_16x16x32_bf16 v[98:101], v[184:187], v[200:203], v[98:101]
	v_mfma_f32_16x16x32_bf16 v[86:89], v[176:179], v[208:211], v[86:89]
	v_mfma_f32_16x16x32_bf16 v[82:85], v[184:187], v[208:211], v[82:85]
	v_mfma_f32_16x16x32_bf16 v[70:73], v[176:179], v[216:219], v[70:73]
	v_mfma_f32_16x16x32_bf16 v[66:69], v[184:187], v[216:219], v[66:69]
	s_setprio 0
	s_barrier
	s_add_i32 s64, s58, s35
	s_mov_b32 m0, s64
	ds_read_b128 v[188:191], v154 offset:16384
	ds_read_b128 v[192:195], v154 offset:17408
	ds_read_b128 v[196:199], v154 offset:18432
	ds_read_b128 v[200:203], v154 offset:19456
	ds_read_b128 v[204:207], v154 offset:20480
	ds_read_b128 v[208:211], v154 offset:21504
	ds_read_b128 v[212:215], v154 offset:22528
	ds_read_b128 v[216:219], v154 offset:23552
	global_load_lds_dwordx4 v132, s[20:21]
	s_add_i32 m0, s64, 0x2000
	s_add_u32 s64, s20, 0xb0000
	s_addc_u32 s65, s21, 0
	s_add_i32 s66, s59, s35
	global_load_lds_dwordx4 v136, s[20:21]
	s_mov_b32 m0, s66
	s_nop 0
	global_load_lds_dwordx4 v132, s[64:65]
	s_add_i32 m0, s66, 0x2000
	s_nop 0
	global_load_lds_dwordx4 v136, s[64:65]
	s_mov_b32 m0, s51
	s_nop 0
	global_load_lds_dwordx4 v130, s[28:29]
	s_mov_b32 m0, s52
	s_nop 0
	global_load_lds_dwordx4 v134, s[28:29]
	s_waitcnt vmcnt(8)
	s_waitcnt lgkmcnt(0)
	s_barrier
	s_setprio 1
	s_waitcnt lgkmcnt(0)
	v_mfma_f32_16x16x32_bf16 v[62:65], v[156:159], v[188:191], v[62:65]
	v_mfma_f32_16x16x32_bf16 v[58:61], v[164:167], v[188:191], v[58:61]
	v_mfma_f32_16x16x32_bf16 v[46:49], v[156:159], v[196:199], v[46:49]
	v_mfma_f32_16x16x32_bf16 v[42:45], v[164:167], v[196:199], v[42:45]
	v_mfma_f32_16x16x32_bf16 v[30:33], v[156:159], v[204:207], v[30:33]
	v_mfma_f32_16x16x32_bf16 v[26:29], v[164:167], v[204:207], v[26:29]
	v_mfma_f32_16x16x32_bf16 v[14:17], v[156:159], v[212:215], v[14:17]
	v_mfma_f32_16x16x32_bf16 v[10:13], v[164:167], v[212:215], v[10:13]
	v_mfma_f32_16x16x32_bf16 v[62:65], v[160:163], v[192:195], v[62:65]
	v_mfma_f32_16x16x32_bf16 v[58:61], v[168:171], v[192:195], v[58:61]
	v_mfma_f32_16x16x32_bf16 v[46:49], v[160:163], v[200:203], v[46:49]
	v_mfma_f32_16x16x32_bf16 v[42:45], v[168:171], v[200:203], v[42:45]
	v_mfma_f32_16x16x32_bf16 v[30:33], v[160:163], v[208:211], v[30:33]
	v_mfma_f32_16x16x32_bf16 v[26:29], v[168:171], v[208:211], v[26:29]
	v_mfma_f32_16x16x32_bf16 v[14:17], v[160:163], v[216:219], v[14:17]
	v_mfma_f32_16x16x32_bf16 v[10:13], v[168:171], v[216:219], v[10:13]
	s_setprio 0
	s_setprio 1
	v_mfma_f32_16x16x32_bf16 v[54:57], v[172:175], v[188:191], v[54:57]
	v_mfma_f32_16x16x32_bf16 v[50:53], v[180:183], v[188:191], v[50:53]
	v_mfma_f32_16x16x32_bf16 v[38:41], v[172:175], v[196:199], v[38:41]
	v_mfma_f32_16x16x32_bf16 v[34:37], v[180:183], v[196:199], v[34:37]
	v_mfma_f32_16x16x32_bf16 v[22:25], v[172:175], v[204:207], v[22:25]
	v_mfma_f32_16x16x32_bf16 v[18:21], v[180:183], v[204:207], v[18:21]
	v_mfma_f32_16x16x32_bf16 v[6:9], v[172:175], v[212:215], v[6:9]
	v_mfma_f32_16x16x32_bf16 v[2:5], v[180:183], v[212:215], v[2:5]
	v_mfma_f32_16x16x32_bf16 v[54:57], v[176:179], v[192:195], v[54:57]
	v_mfma_f32_16x16x32_bf16 v[50:53], v[184:187], v[192:195], v[50:53]
	v_mfma_f32_16x16x32_bf16 v[38:41], v[176:179], v[200:203], v[38:41]
	v_mfma_f32_16x16x32_bf16 v[34:37], v[184:187], v[200:203], v[34:37]
	v_mfma_f32_16x16x32_bf16 v[22:25], v[176:179], v[208:211], v[22:25]
	v_mfma_f32_16x16x32_bf16 v[18:21], v[184:187], v[208:211], v[18:21]
	v_mfma_f32_16x16x32_bf16 v[6:9], v[176:179], v[216:219], v[6:9]
	v_mfma_f32_16x16x32_bf16 v[2:5], v[184:187], v[216:219], v[2:5]
	s_setprio 0
	s_barrier
	s_add_i32 s64, 0, 0x18000
	v_add_u32_e32 v155, s64, v153
	s_add_i32 s65, 0, 0x1c000
	ds_read_b128 v[156:159], v155
	ds_read_b128 v[160:163], v155 offset:1024
	ds_read_b128 v[164:167], v155 offset:2048
	ds_read_b128 v[168:171], v155 offset:3072
	v_add_u32_e32 v155, s65, v153
	ds_read_b128 v[172:175], v155
	ds_read_b128 v[176:179], v155 offset:1024
	ds_read_b128 v[180:183], v155 offset:2048
	ds_read_b128 v[184:187], v155 offset:3072
	s_add_u32 s98, s28, 0xb0000
	s_addc_u32 s99, s29, 0
	s_mov_b32 m0, s53
	ds_read_b128 v[188:191], v154 offset:32768
	ds_read_b128 v[192:195], v154 offset:33792
	ds_read_b128 v[196:199], v154 offset:34816
	ds_read_b128 v[200:203], v154 offset:35840
	ds_read_b128 v[204:207], v154 offset:36864
	ds_read_b128 v[208:211], v154 offset:37888
	ds_read_b128 v[212:215], v154 offset:38912
	ds_read_b128 v[216:219], v154 offset:39936
	global_load_lds_dwordx4 v130, s[98:99]
	s_mov_b32 m0, s54
	s_nop 0
	global_load_lds_dwordx4 v134, s[98:99]
	s_waitcnt vmcnt(8)
	s_waitcnt lgkmcnt(0)
	s_barrier
	s_setprio 1
	s_waitcnt lgkmcnt(0)
	v_mfma_f32_16x16x32_bf16 v[126:129], v[156:159], v[188:191], v[126:129]
	v_mfma_f32_16x16x32_bf16 v[122:125], v[164:167], v[188:191], v[122:125]
	v_mfma_f32_16x16x32_bf16 v[110:113], v[156:159], v[196:199], v[110:113]
	v_mfma_f32_16x16x32_bf16 v[106:109], v[164:167], v[196:199], v[106:109]
	v_mfma_f32_16x16x32_bf16 v[94:97], v[156:159], v[204:207], v[94:97]
	v_mfma_f32_16x16x32_bf16 v[90:93], v[164:167], v[204:207], v[90:93]
	v_mfma_f32_16x16x32_bf16 v[78:81], v[156:159], v[212:215], v[78:81]
	v_mfma_f32_16x16x32_bf16 v[74:77], v[164:167], v[212:215], v[74:77]
	v_mfma_f32_16x16x32_bf16 v[126:129], v[160:163], v[192:195], v[126:129]
	v_mfma_f32_16x16x32_bf16 v[122:125], v[168:171], v[192:195], v[122:125]
	v_mfma_f32_16x16x32_bf16 v[110:113], v[160:163], v[200:203], v[110:113]
	v_mfma_f32_16x16x32_bf16 v[106:109], v[168:171], v[200:203], v[106:109]
	v_mfma_f32_16x16x32_bf16 v[94:97], v[160:163], v[208:211], v[94:97]
	v_mfma_f32_16x16x32_bf16 v[90:93], v[168:171], v[208:211], v[90:93]
	v_mfma_f32_16x16x32_bf16 v[78:81], v[160:163], v[216:219], v[78:81]
	v_mfma_f32_16x16x32_bf16 v[74:77], v[168:171], v[216:219], v[74:77]
	s_setprio 0
	s_setprio 1
	v_mfma_f32_16x16x32_bf16 v[118:121], v[172:175], v[188:191], v[118:121]
	v_mfma_f32_16x16x32_bf16 v[114:117], v[180:183], v[188:191], v[114:117]
	v_mfma_f32_16x16x32_bf16 v[102:105], v[172:175], v[196:199], v[102:105]
	v_mfma_f32_16x16x32_bf16 v[98:101], v[180:183], v[196:199], v[98:101]
	v_mfma_f32_16x16x32_bf16 v[86:89], v[172:175], v[204:207], v[86:89]
	v_mfma_f32_16x16x32_bf16 v[82:85], v[180:183], v[204:207], v[82:85]
	v_mfma_f32_16x16x32_bf16 v[70:73], v[172:175], v[212:215], v[70:73]
	v_mfma_f32_16x16x32_bf16 v[66:69], v[180:183], v[212:215], v[66:69]
	v_mfma_f32_16x16x32_bf16 v[118:121], v[176:179], v[192:195], v[118:121]
	v_mfma_f32_16x16x32_bf16 v[114:117], v[184:187], v[192:195], v[114:117]
	v_mfma_f32_16x16x32_bf16 v[102:105], v[176:179], v[200:203], v[102:105]
	v_mfma_f32_16x16x32_bf16 v[98:101], v[184:187], v[200:203], v[98:101]
	v_mfma_f32_16x16x32_bf16 v[86:89], v[176:179], v[208:211], v[86:89]
	v_mfma_f32_16x16x32_bf16 v[82:85], v[184:187], v[208:211], v[82:85]
	v_mfma_f32_16x16x32_bf16 v[70:73], v[176:179], v[216:219], v[70:73]
	v_mfma_f32_16x16x32_bf16 v[66:69], v[184:187], v[216:219], v[66:69]
	s_setprio 0
	s_barrier
	s_add_i32 s98, s64, s35
	s_add_i32 m0, s98, 0xffffff80
	ds_read_b128 v[188:191], v154 offset:49152
	ds_read_b128 v[192:195], v154 offset:50176
	ds_read_b128 v[196:199], v154 offset:51200
	ds_read_b128 v[200:203], v154 offset:52224
	ds_read_b128 v[204:207], v154 offset:53248
	ds_read_b128 v[208:211], v154 offset:54272
	ds_read_b128 v[212:215], v154 offset:55296
	ds_read_b128 v[216:219], v154 offset:56320
	global_load_lds_dwordx4 v132, s[20:21] offset:128
	s_add_i32 m0, s98, 0x1f80
	s_add_i32 s98, s65, s35
	global_load_lds_dwordx4 v136, s[20:21] offset:128
	s_add_u32 s20, s20, 0xb0080
	s_addc_u32 s21, s21, 0
	s_mov_b32 m0, s98
	s_nop 0
	global_load_lds_dwordx4 v132, s[20:21]
	s_add_i32 m0, s98, 0x2000
	s_nop 0
	global_load_lds_dwordx4 v136, s[20:21]
	s_add_i32 m0, s56, 0xffffff80
	s_nop 0
	global_load_lds_dwordx4 v130, s[28:29] offset:128
	s_add_i32 m0, s57, 0xffffff80
	s_nop 0
	global_load_lds_dwordx4 v134, s[28:29] offset:128
	s_waitcnt vmcnt(8)
	s_waitcnt lgkmcnt(0)
	s_barrier
	s_setprio 1
	s_waitcnt lgkmcnt(0)
	v_mfma_f32_16x16x32_bf16 v[62:65], v[156:159], v[188:191], v[62:65]
	v_mfma_f32_16x16x32_bf16 v[58:61], v[164:167], v[188:191], v[58:61]
	v_mfma_f32_16x16x32_bf16 v[46:49], v[156:159], v[196:199], v[46:49]
	v_mfma_f32_16x16x32_bf16 v[42:45], v[164:167], v[196:199], v[42:45]
	v_mfma_f32_16x16x32_bf16 v[30:33], v[156:159], v[204:207], v[30:33]
	v_mfma_f32_16x16x32_bf16 v[26:29], v[164:167], v[204:207], v[26:29]
	v_mfma_f32_16x16x32_bf16 v[14:17], v[156:159], v[212:215], v[14:17]
	v_mfma_f32_16x16x32_bf16 v[10:13], v[164:167], v[212:215], v[10:13]
	v_mfma_f32_16x16x32_bf16 v[62:65], v[160:163], v[192:195], v[62:65]
	v_mfma_f32_16x16x32_bf16 v[58:61], v[168:171], v[192:195], v[58:61]
	v_mfma_f32_16x16x32_bf16 v[46:49], v[160:163], v[200:203], v[46:49]
	v_mfma_f32_16x16x32_bf16 v[42:45], v[168:171], v[200:203], v[42:45]
	v_mfma_f32_16x16x32_bf16 v[30:33], v[160:163], v[208:211], v[30:33]
	v_mfma_f32_16x16x32_bf16 v[26:29], v[168:171], v[208:211], v[26:29]
	v_mfma_f32_16x16x32_bf16 v[14:17], v[160:163], v[216:219], v[14:17]
	v_mfma_f32_16x16x32_bf16 v[10:13], v[168:171], v[216:219], v[10:13]
	s_setprio 0
	s_setprio 1
	v_mfma_f32_16x16x32_bf16 v[54:57], v[172:175], v[188:191], v[54:57]
	v_mfma_f32_16x16x32_bf16 v[50:53], v[180:183], v[188:191], v[50:53]
	v_mfma_f32_16x16x32_bf16 v[38:41], v[172:175], v[196:199], v[38:41]
	v_mfma_f32_16x16x32_bf16 v[34:37], v[180:183], v[196:199], v[34:37]
	v_mfma_f32_16x16x32_bf16 v[22:25], v[172:175], v[204:207], v[22:25]
	v_mfma_f32_16x16x32_bf16 v[18:21], v[180:183], v[204:207], v[18:21]
	v_mfma_f32_16x16x32_bf16 v[6:9], v[172:175], v[212:215], v[6:9]
	v_mfma_f32_16x16x32_bf16 v[2:5], v[180:183], v[212:215], v[2:5]
	v_mfma_f32_16x16x32_bf16 v[54:57], v[176:179], v[192:195], v[54:57]
	v_mfma_f32_16x16x32_bf16 v[50:53], v[184:187], v[192:195], v[50:53]
	v_mfma_f32_16x16x32_bf16 v[38:41], v[176:179], v[200:203], v[38:41]
	v_mfma_f32_16x16x32_bf16 v[34:37], v[184:187], v[200:203], v[34:37]
	v_mfma_f32_16x16x32_bf16 v[22:25], v[176:179], v[208:211], v[22:25]
	v_mfma_f32_16x16x32_bf16 v[18:21], v[184:187], v[208:211], v[18:21]
	v_mfma_f32_16x16x32_bf16 v[6:9], v[176:179], v[216:219], v[6:9]
	v_mfma_f32_16x16x32_bf16 v[2:5], v[184:187], v[216:219], v[2:5]
	s_setprio 0
	s_barrier
	s_add_i32 s63, s63, 2
	s_add_u32 s18, s18, 0x100
	s_addc_u32 s19, s19, 0
	s_cmp_gt_u32 s63, 41
	s_cbranch_scc0 .LBB0_730
	s_add_u32 s18, s15, 0xffffff00
	s_addc_u32 s19, s62, -1
	s_and_b64 vcc, exec, s[4:5]
	s_cbranch_vccnz .LBB0_733
	v_mov_b32_e32 v2, 0
	v_mov_b32_e32 v3, 0
	v_mov_b64_e32 v[4:5], v[2:3]
	v_mov_b64_e32 v[6:7], v[2:3]
	v_mov_b64_e32 v[8:9], v[2:3]
	v_mov_b64_e32 v[10:11], v[2:3]
	v_mov_b64_e32 v[12:13], v[2:3]
	v_mov_b64_e32 v[14:15], v[2:3]
	v_mov_b64_e32 v[16:17], v[2:3]
	v_mov_b64_e32 v[18:19], v[2:3]
	v_mov_b64_e32 v[20:21], v[2:3]
	v_mov_b64_e32 v[22:23], v[2:3]
	v_mov_b64_e32 v[24:25], v[2:3]
	v_mov_b64_e32 v[26:27], v[2:3]
	v_mov_b64_e32 v[28:29], v[2:3]
	v_mov_b64_e32 v[30:31], v[2:3]
	v_mov_b64_e32 v[32:33], v[2:3]
	v_mov_b64_e32 v[34:35], v[2:3]
	v_mov_b64_e32 v[36:37], v[2:3]
	v_mov_b64_e32 v[38:39], v[2:3]
	v_mov_b64_e32 v[40:41], v[2:3]
	v_mov_b64_e32 v[42:43], v[2:3]
	v_mov_b64_e32 v[44:45], v[2:3]
	v_mov_b64_e32 v[46:47], v[2:3]
	v_mov_b64_e32 v[48:49], v[2:3]
	v_mov_b64_e32 v[50:51], v[2:3]
	v_mov_b64_e32 v[52:53], v[2:3]
	v_mov_b64_e32 v[54:55], v[2:3]
	v_mov_b64_e32 v[56:57], v[2:3]
	v_mov_b64_e32 v[58:59], v[2:3]
	v_mov_b64_e32 v[60:61], v[2:3]
	v_mov_b64_e32 v[62:63], v[2:3]
	v_mov_b64_e32 v[64:65], v[2:3]
	v_mov_b64_e32 v[66:67], v[2:3]
	v_mov_b64_e32 v[68:69], v[2:3]
	v_mov_b64_e32 v[70:71], v[2:3]
	v_mov_b64_e32 v[72:73], v[2:3]
	v_mov_b64_e32 v[74:75], v[2:3]
	v_mov_b64_e32 v[76:77], v[2:3]
	v_mov_b64_e32 v[78:79], v[2:3]
	v_mov_b64_e32 v[80:81], v[2:3]
	v_mov_b64_e32 v[82:83], v[2:3]
	v_mov_b64_e32 v[84:85], v[2:3]
	v_mov_b64_e32 v[86:87], v[2:3]
	v_mov_b64_e32 v[88:89], v[2:3]
	v_mov_b64_e32 v[90:91], v[2:3]
	v_mov_b64_e32 v[92:93], v[2:3]
	v_mov_b64_e32 v[94:95], v[2:3]
	v_mov_b64_e32 v[96:97], v[2:3]
	v_mov_b64_e32 v[98:99], v[2:3]
	v_mov_b64_e32 v[100:101], v[2:3]
	v_mov_b64_e32 v[102:103], v[2:3]
	v_mov_b64_e32 v[104:105], v[2:3]
	v_mov_b64_e32 v[106:107], v[2:3]
	v_mov_b64_e32 v[108:109], v[2:3]
	v_mov_b64_e32 v[110:111], v[2:3]
	v_mov_b64_e32 v[112:113], v[2:3]
	v_mov_b64_e32 v[114:115], v[2:3]
	v_mov_b64_e32 v[116:117], v[2:3]
	v_mov_b64_e32 v[118:119], v[2:3]
	v_mov_b64_e32 v[120:121], v[2:3]
	v_mov_b64_e32 v[122:123], v[2:3]
	v_mov_b64_e32 v[124:125], v[2:3]
	v_mov_b64_e32 v[126:127], v[2:3]
	v_mov_b64_e32 v[128:129], v[2:3]
	s_mov_b32 s8, s60
	s_mov_b32 s50, s61
	s_mov_b64 s[10:11], s[16:17]
	s_mov_b32 s55, s14
	s_branch .LBB0_734

.LBB0_861:
	s_ashr_i32 s65, s64, 31
	s_lshl_b64 s[22:23], s[64:65], 19
	s_add_u32 s66, s80, s22
	s_addc_u32 s67, s81, s23
	s_and_b64 s[22:23], s[6:7], exec
	s_cselect_b32 s9, s67, s13
	s_cselect_b32 s11, s66, s12
	s_ashr_i32 s63, s62, 31
	s_lshl_b64 s[22:23], s[62:63], 19
	s_add_u32 s78, s84, s22
	s_addc_u32 s79, s85, s23
	s_and_b64 s[22:23], s[6:7], exec
	s_cselect_b32 s14, s79, s29
	s_cselect_b32 s22, s78, s28
	s_add_u32 s12, s12, 0x40080
	s_addc_u32 s13, s13, 0
	s_add_u32 s23, s28, 0x100
	v_mov_b32_e32 v2, 0
	v_mov_b32_e32 v3, 0
	v_mov_b64_e32 v[4:5], v[2:3]
	v_mov_b64_e32 v[6:7], v[2:3]
	v_mov_b64_e32 v[8:9], v[2:3]
	v_mov_b64_e32 v[10:11], v[2:3]
	v_mov_b64_e32 v[12:13], v[2:3]
	v_mov_b64_e32 v[14:15], v[2:3]
	v_mov_b64_e32 v[16:17], v[2:3]
	v_mov_b64_e32 v[18:19], v[2:3]
	v_mov_b64_e32 v[20:21], v[2:3]
	v_mov_b64_e32 v[22:23], v[2:3]
	v_mov_b64_e32 v[24:25], v[2:3]
	v_mov_b64_e32 v[26:27], v[2:3]
	v_mov_b64_e32 v[28:29], v[2:3]
	v_mov_b64_e32 v[30:31], v[2:3]
	v_mov_b64_e32 v[32:33], v[2:3]
	v_mov_b64_e32 v[34:35], v[2:3]
	v_mov_b64_e32 v[36:37], v[2:3]
	v_mov_b64_e32 v[38:39], v[2:3]
	v_mov_b64_e32 v[40:41], v[2:3]
	v_mov_b64_e32 v[42:43], v[2:3]
	v_mov_b64_e32 v[44:45], v[2:3]
	v_mov_b64_e32 v[46:47], v[2:3]
	v_mov_b64_e32 v[48:49], v[2:3]
	v_mov_b64_e32 v[50:51], v[2:3]
	v_mov_b64_e32 v[52:53], v[2:3]
	v_mov_b64_e32 v[54:55], v[2:3]
	v_mov_b64_e32 v[56:57], v[2:3]
	v_mov_b64_e32 v[58:59], v[2:3]
	v_mov_b64_e32 v[60:61], v[2:3]
	v_mov_b64_e32 v[62:63], v[2:3]
	v_mov_b64_e32 v[64:65], v[2:3]
	v_mov_b64_e32 v[66:67], v[2:3]
	v_mov_b64_e32 v[68:69], v[2:3]
	v_mov_b64_e32 v[70:71], v[2:3]
	v_mov_b64_e32 v[72:73], v[2:3]
	v_mov_b64_e32 v[74:75], v[2:3]
	v_mov_b64_e32 v[76:77], v[2:3]
	v_mov_b64_e32 v[78:79], v[2:3]
	v_mov_b64_e32 v[80:81], v[2:3]
	v_mov_b64_e32 v[82:83], v[2:3]
	v_mov_b64_e32 v[84:85], v[2:3]
	v_mov_b64_e32 v[86:87], v[2:3]
	v_mov_b64_e32 v[88:89], v[2:3]
	v_mov_b64_e32 v[90:91], v[2:3]
	v_mov_b64_e32 v[92:93], v[2:3]
	v_mov_b64_e32 v[94:95], v[2:3]
	v_mov_b64_e32 v[96:97], v[2:3]
	v_mov_b64_e32 v[98:99], v[2:3]
	v_mov_b64_e32 v[100:101], v[2:3]
	v_mov_b64_e32 v[102:103], v[2:3]
	v_mov_b64_e32 v[104:105], v[2:3]
	v_mov_b64_e32 v[106:107], v[2:3]
	v_mov_b64_e32 v[108:109], v[2:3]
	v_mov_b64_e32 v[110:111], v[2:3]
	v_mov_b64_e32 v[112:113], v[2:3]
	v_mov_b64_e32 v[114:115], v[2:3]
	v_mov_b64_e32 v[116:117], v[2:3]
	v_mov_b64_e32 v[118:119], v[2:3]
	v_mov_b64_e32 v[120:121], v[2:3]
	v_mov_b64_e32 v[122:123], v[2:3]
	v_mov_b64_e32 v[124:125], v[2:3]
	v_mov_b64_e32 v[126:127], v[2:3]
	v_mov_b64_e32 v[128:129], v[2:3]
	s_addc_u32 s24, s29, 0
	s_mov_b32 s34, -2

.LBB0_1653:
	s_ashr_i32 s15, s14, 31
	s_lshl_b64 s[16:17], s[14:15], 19
	s_add_u32 s16, s80, s16
	s_addc_u32 s17, s81, s17
	s_and_b64 s[18:19], s[2:3], exec
	s_cselect_b32 s15, s17, s31
	s_cselect_b32 s47, s16, s30
	s_ashr_i32 s13, s12, 31
	s_lshl_b64 s[18:19], s[12:13], 19
	s_add_u32 s18, s23, s18
	s_addc_u32 s19, s24, s19
	s_and_b64 s[36:37], s[2:3], exec
	s_cselect_b32 s13, s19, s29
	s_cselect_b32 s48, s18, s28
	s_add_u32 s36, s30, 0x40080
	s_addc_u32 s37, s31, 0
	s_add_u32 s49, s28, 0x100
	v_mov_b32_e32 v2, 0
	v_mov_b32_e32 v3, 0
	v_mov_b64_e32 v[4:5], v[2:3]
	v_mov_b64_e32 v[6:7], v[2:3]
	v_mov_b64_e32 v[8:9], v[2:3]
	v_mov_b64_e32 v[10:11], v[2:3]
	v_mov_b64_e32 v[12:13], v[2:3]
	v_mov_b64_e32 v[14:15], v[2:3]
	v_mov_b64_e32 v[16:17], v[2:3]
	v_mov_b64_e32 v[18:19], v[2:3]
	v_mov_b64_e32 v[20:21], v[2:3]
	v_mov_b64_e32 v[22:23], v[2:3]
	v_mov_b64_e32 v[24:25], v[2:3]
	v_mov_b64_e32 v[26:27], v[2:3]
	v_mov_b64_e32 v[28:29], v[2:3]
	v_mov_b64_e32 v[30:31], v[2:3]
	v_mov_b64_e32 v[32:33], v[2:3]
	v_mov_b64_e32 v[34:35], v[2:3]
	v_mov_b64_e32 v[36:37], v[2:3]
	v_mov_b64_e32 v[38:39], v[2:3]
	v_mov_b64_e32 v[40:41], v[2:3]
	v_mov_b64_e32 v[42:43], v[2:3]
	v_mov_b64_e32 v[44:45], v[2:3]
	v_mov_b64_e32 v[46:47], v[2:3]
	v_mov_b64_e32 v[48:49], v[2:3]
	v_mov_b64_e32 v[50:51], v[2:3]
	v_mov_b64_e32 v[52:53], v[2:3]
	v_mov_b64_e32 v[54:55], v[2:3]
	v_mov_b64_e32 v[56:57], v[2:3]
	v_mov_b64_e32 v[58:59], v[2:3]
	v_mov_b64_e32 v[60:61], v[2:3]
	v_mov_b64_e32 v[62:63], v[2:3]
	v_mov_b64_e32 v[64:65], v[2:3]
	v_mov_b64_e32 v[66:67], v[2:3]
	v_mov_b64_e32 v[68:69], v[2:3]
	v_mov_b64_e32 v[70:71], v[2:3]
	v_mov_b64_e32 v[72:73], v[2:3]
	v_mov_b64_e32 v[74:75], v[2:3]
	v_mov_b64_e32 v[76:77], v[2:3]
	v_mov_b64_e32 v[78:79], v[2:3]
	v_mov_b64_e32 v[80:81], v[2:3]
	v_mov_b64_e32 v[82:83], v[2:3]
	v_mov_b64_e32 v[84:85], v[2:3]
	v_mov_b64_e32 v[86:87], v[2:3]
	v_mov_b64_e32 v[88:89], v[2:3]
	v_mov_b64_e32 v[90:91], v[2:3]
	v_mov_b64_e32 v[92:93], v[2:3]
	v_mov_b64_e32 v[94:95], v[2:3]
	v_mov_b64_e32 v[96:97], v[2:3]
	v_mov_b64_e32 v[98:99], v[2:3]
	v_mov_b64_e32 v[100:101], v[2:3]
	v_mov_b64_e32 v[102:103], v[2:3]
	v_mov_b64_e32 v[104:105], v[2:3]
	v_mov_b64_e32 v[106:107], v[2:3]
	v_mov_b64_e32 v[108:109], v[2:3]
	v_mov_b64_e32 v[110:111], v[2:3]
	v_mov_b64_e32 v[112:113], v[2:3]
	v_mov_b64_e32 v[114:115], v[2:3]
	v_mov_b64_e32 v[116:117], v[2:3]
	v_mov_b64_e32 v[118:119], v[2:3]
	v_mov_b64_e32 v[120:121], v[2:3]
	v_mov_b64_e32 v[122:123], v[2:3]
	v_mov_b64_e32 v[124:125], v[2:3]
	v_mov_b64_e32 v[126:127], v[2:3]
	v_mov_b64_e32 v[128:129], v[2:3]
	s_addc_u32 s50, s29, 0
	s_mov_b32 s51, -2
	s_waitcnt vmcnt(0)

.LBB0_1686:
	v_lshlrev_b32_e32 v13, 2, v1
	s_lshl_b32 s34, s8, 6
	v_lshl_or_b32 v12, v1, 6, v130
	v_and_b32_e32 v169, 32, v13
	s_lshl_b32 s9, s9, 5
	s_lshl_b32 s8, s8, 13
	s_and_b32 s35, s9, 0x60
	v_bitop3_b32 v12, v12, s8, v169 bitop3:0xde
	s_mov_b64 s[8:9], 0x80
	s_add_i32 m0, s29, 0x18000
	v_lshl_add_u64 v[8:9], v[8:9], 0, s[8:9]
	s_waitcnt vmcnt(2)
	s_barrier
	global_load_lds_dwordx4 v[8:9], off
	v_lshl_add_u64 v[6:7], v[6:7], 0, s[8:9]
	s_add_i32 m0, s29, 0x1a000
	s_add_i32 s36, s29, 0x8000
	s_add_i32 s37, s29, 0xa000
	global_load_lds_dwordx4 v[6:7], off
	v_lshl_add_u64 v[4:5], v[4:5], 0, s[8:9]
	s_mov_b32 m0, s36
	s_add_u32 s10, s4, 0x30080
	global_load_lds_dwordx4 v[4:5], off
	v_lshl_add_u64 v[2:3], v[2:3], 0, s[8:9]
	s_mov_b32 m0, s37
	s_addc_u32 s11, s5, 0
	global_load_lds_dwordx4 v[2:3], off
	s_add_i32 m0, s29, 0x1c000
	v_lshl_add_u64 v[2:3], s[10:11], 0, v[136:137]
	global_load_lds_dwordx4 v[2:3], off
	v_lshl_add_u64 v[2:3], s[10:11], 0, v[140:141]
	s_add_i32 m0, s29, 0x1e000
	s_add_u32 s10, s26, s21
	global_load_lds_dwordx4 v[2:3], off
	v_add_u16_e32 v2, v166, v167
	v_lshrrev_b16_e32 v4, 1, v2
	s_addc_u32 s11, s27, s20
	v_add_lshl_u32 v2, v10, v4, 1
	v_mov_b32_e32 v3, v137
	v_lshl_add_u64 v[2:3], s[10:11], 0, v[2:3]
	s_mov_b64 s[12:13], 0xd630080
	v_lshl_add_u64 v[142:143], v[2:3], 0, s[12:13]
	v_add_lshl_u32 v2, v11, v4, 1
	v_mov_b32_e32 v3, v137
	v_lshl_add_u64 v[2:3], s[10:11], 0, v[2:3]
	v_lshl_add_u64 v[144:145], v[2:3], 0, s[12:13]
	s_add_u32 s12, s26, s23
	s_addc_u32 s13, s27, s22
	s_add_u32 s38, s12, 0x1d00100
	s_waitcnt vmcnt(6)
	s_addc_u32 s39, s13, 0
	s_add_i32 s19, 0, 0x10000
	s_add_i32 s18, 0, 0x14000
	s_add_i32 s24, 0, 0x18000
	s_add_i32 s25, 0, 0x1c000
	v_lshl_or_b32 v13, s35, 7, v170
	s_add_i32 s43, s19, s14
	s_add_i32 s45, s18, s14
	s_add_i32 s47, s24, s14
	s_add_i32 s49, s25, s14
	s_mov_b32 s40, -2
	s_mov_b64 s[12:13], 0
	v_add_u32_e32 v131, s19, v13
	v_add_u32_e32 v146, s18, v13
	v_add_u32_e32 v147, 0, v12
	s_add_i32 s41, s29, 0xc000
	s_add_i32 s42, s29, 0xe000
	s_add_i32 s44, s43, 0x2000
	s_add_i32 s46, s45, 0x2000
	v_add_u32_e32 v148, s24, v13
	v_add_u32_e32 v149, s25, v13
	s_add_i32 s48, s47, 0x2000
	s_add_i32 s50, s49, 0x2000
	v_mov_b32_e32 v2, v137
	v_mov_b32_e32 v3, v137
	v_mov_b64_e32 v[4:5], v[2:3]
	v_mov_b64_e32 v[6:7], v[2:3]
	v_mov_b64_e32 v[8:9], v[2:3]
	v_mov_b64_e32 v[10:11], v[2:3]
	v_mov_b64_e32 v[12:13], v[2:3]
	v_mov_b64_e32 v[14:15], v[2:3]
	v_mov_b64_e32 v[16:17], v[2:3]
	v_mov_b64_e32 v[18:19], v[2:3]
	v_mov_b64_e32 v[20:21], v[2:3]
	v_mov_b64_e32 v[22:23], v[2:3]
	v_mov_b64_e32 v[24:25], v[2:3]
	v_mov_b64_e32 v[26:27], v[2:3]
	v_mov_b64_e32 v[28:29], v[2:3]
	v_mov_b64_e32 v[30:31], v[2:3]
	v_mov_b64_e32 v[32:33], v[2:3]
	v_mov_b64_e32 v[34:35], v[2:3]
	v_mov_b64_e32 v[36:37], v[2:3]
	v_mov_b64_e32 v[38:39], v[2:3]
	v_mov_b64_e32 v[40:41], v[2:3]
	v_mov_b64_e32 v[42:43], v[2:3]
	v_mov_b64_e32 v[44:45], v[2:3]
	v_mov_b64_e32 v[46:47], v[2:3]
	v_mov_b64_e32 v[48:49], v[2:3]
	v_mov_b64_e32 v[50:51], v[2:3]
	v_mov_b64_e32 v[52:53], v[2:3]
	v_mov_b64_e32 v[54:55], v[2:3]
	v_mov_b64_e32 v[56:57], v[2:3]
	v_mov_b64_e32 v[58:59], v[2:3]
	v_mov_b64_e32 v[60:61], v[2:3]
	v_mov_b64_e32 v[62:63], v[2:3]
	v_mov_b64_e32 v[64:65], v[2:3]
	v_mov_b64_e32 v[66:67], v[2:3]
	v_mov_b64_e32 v[68:69], v[2:3]
	v_mov_b64_e32 v[70:71], v[2:3]
	v_mov_b64_e32 v[72:73], v[2:3]
	v_mov_b64_e32 v[74:75], v[2:3]
	v_mov_b64_e32 v[76:77], v[2:3]
	v_mov_b64_e32 v[78:79], v[2:3]
	v_mov_b64_e32 v[80:81], v[2:3]
	v_mov_b64_e32 v[82:83], v[2:3]
	v_mov_b64_e32 v[84:85], v[2:3]
	v_mov_b64_e32 v[86:87], v[2:3]
	v_mov_b64_e32 v[88:89], v[2:3]
	v_mov_b64_e32 v[90:91], v[2:3]
	v_mov_b64_e32 v[92:93], v[2:3]
	v_mov_b64_e32 v[94:95], v[2:3]
	v_mov_b64_e32 v[96:97], v[2:3]
	v_mov_b64_e32 v[98:99], v[2:3]
	v_mov_b64_e32 v[100:101], v[2:3]
	v_mov_b64_e32 v[102:103], v[2:3]
	v_mov_b64_e32 v[104:105], v[2:3]
	v_mov_b64_e32 v[106:107], v[2:3]
	v_mov_b64_e32 v[108:109], v[2:3]
	v_mov_b64_e32 v[110:111], v[2:3]
	v_mov_b64_e32 v[112:113], v[2:3]
	v_mov_b64_e32 v[114:115], v[2:3]
	v_mov_b64_e32 v[116:117], v[2:3]
	v_mov_b64_e32 v[118:119], v[2:3]
	v_mov_b64_e32 v[120:121], v[2:3]
	v_mov_b64_e32 v[122:123], v[2:3]
	v_mov_b64_e32 v[124:125], v[2:3]
	v_mov_b64_e32 v[126:127], v[2:3]
	v_mov_b64_e32 v[128:129], v[2:3]
	s_waitcnt vmcnt(0)
	s_barrier

.LBB0_1778:
	v_and_b32_e32 v1, 15, v0
	v_and_b32_e32 v14, 48, v0
	v_lshlrev_b32_e32 v16, 2, v0
	s_sext_i32_i8 s6, s2
	v_lshl_or_b32 v15, v1, 6, v14
	s_lshl_b32 s2, s22, 13
	v_and_b32_e32 v16, 32, v16
	s_mov_b64 s[12:13], 0x80
	s_and_b32 s23, s7, 3
	v_bitop3_b32 v15, v15, s2, v16 bitop3:0xde
	v_lshlrev_b32_e32 v17, 6, v0
	s_movk_i32 s2, 0x3c0
	s_add_i32 m0, s1, 0x18000
	v_lshl_add_u64 v[8:9], v[8:9], 0, s[12:13]
	v_and_or_b32 v14, v17, s2, v14
	s_lshl_b32 s2, s23, 12
	s_waitcnt vmcnt(2)
	s_barrier
	global_load_lds_dwordx4 v[8:9], off
	v_lshl_add_u64 v[6:7], v[6:7], 0, s[12:13]
	s_add_i32 m0, s1, 0x1a000
	s_add_i32 s46, s1, 0x8000
	s_add_i32 s47, s1, 0xa000
	global_load_lds_dwordx4 v[6:7], off
	v_lshl_add_u64 v[4:5], v[4:5], 0, s[12:13]
	s_mov_b32 m0, s46
	s_add_u32 s4, s28, 0x40080
	global_load_lds_dwordx4 v[4:5], off
	v_lshl_add_u64 v[2:3], v[2:3], 0, s[12:13]
	s_mov_b32 m0, s47
	s_addc_u32 s5, s29, 0
	global_load_lds_dwordx4 v[2:3], off
	s_add_i32 m0, s1, 0x1c000
	v_lshl_add_u64 v[2:3], s[4:5], 0, v[132:133]
	global_load_lds_dwordx4 v[2:3], off
	v_lshl_add_u64 v[2:3], s[4:5], 0, v[136:137]
	s_add_i32 m0, s1, 0x1e000
	v_lshlrev_b32_e32 v4, 11, v12
	global_load_lds_dwordx4 v[2:3], off
	v_lshlrev_b32_e32 v2, 8, v0
	v_and_b32_e32 v2, 0x18000, v2
	v_or3_b32 v2, v10, v2, v4
	v_bitop3_b32 v153, s2, v14, v16 bitop3:0xf6
	s_mov_b64 s[2:3], 0x40080
	v_add_u32_e32 v2, v2, v11
	v_mov_b32_e32 v3, v133
	v_lshl_add_u64 v[140:141], v[2:3], 0, s[2:3]
	v_lshlrev_b32_e32 v2, 4, v13
	v_and_b32_e32 v2, 0x38000, v2
	s_waitcnt vmcnt(6)
	v_or3_b32 v2, v10, v2, v4
	v_add_u32_e32 v2, v2, v11
	v_lshl_or_b32 v152, s22, 6, v1
	v_lshl_add_u64 v[142:143], v[2:3], 0, s[2:3]
	v_mov_b64_e32 v[144:145], 0x100
	v_mov_b64_e32 v[146:147], 0xff
	s_add_i32 s48, 0, 0x10000
	s_add_i32 s49, 0, 0x14000
	v_add_u32_e32 v154, 0, v15
	v_mov_b32_e32 v4, v133
	v_mov_b32_e32 v5, v133
	v_mov_b64_e32 v[6:7], v[4:5]
	v_mov_b64_e32 v[8:9], v[4:5]
	v_mov_b64_e32 v[10:11], v[4:5]
	v_mov_b64_e32 v[12:13], v[4:5]
	v_mov_b64_e32 v[14:15], v[4:5]
	v_mov_b64_e32 v[16:17], v[4:5]
	v_mov_b64_e32 v[18:19], v[4:5]
	v_mov_b64_e32 v[20:21], v[4:5]
	v_mov_b64_e32 v[22:23], v[4:5]
	v_mov_b64_e32 v[24:25], v[4:5]
	v_mov_b64_e32 v[26:27], v[4:5]
	v_mov_b64_e32 v[28:29], v[4:5]
	v_mov_b64_e32 v[30:31], v[4:5]
	v_mov_b64_e32 v[32:33], v[4:5]
	v_mov_b64_e32 v[34:35], v[4:5]
	v_mov_b64_e32 v[36:37], v[4:5]
	v_mov_b64_e32 v[38:39], v[4:5]
	v_mov_b64_e32 v[40:41], v[4:5]
	v_mov_b64_e32 v[42:43], v[4:5]
	v_mov_b64_e32 v[44:45], v[4:5]
	v_mov_b64_e32 v[46:47], v[4:5]
	v_mov_b64_e32 v[48:49], v[4:5]
	v_mov_b64_e32 v[50:51], v[4:5]
	v_mov_b64_e32 v[52:53], v[4:5]
	v_mov_b64_e32 v[54:55], v[4:5]
	v_mov_b64_e32 v[56:57], v[4:5]
	v_mov_b64_e32 v[58:59], v[4:5]
	v_mov_b64_e32 v[60:61], v[4:5]
	v_mov_b64_e32 v[62:63], v[4:5]
	v_mov_b64_e32 v[64:65], v[4:5]
	v_mov_b64_e32 v[66:67], v[4:5]
	v_mov_b64_e32 v[68:69], v[4:5]
	v_mov_b64_e32 v[70:71], v[4:5]
	v_mov_b64_e32 v[72:73], v[4:5]
	v_mov_b64_e32 v[74:75], v[4:5]
	v_mov_b64_e32 v[76:77], v[4:5]
	v_mov_b64_e32 v[78:79], v[4:5]
	v_mov_b64_e32 v[80:81], v[4:5]
	v_mov_b64_e32 v[82:83], v[4:5]
	v_mov_b64_e32 v[84:85], v[4:5]
	v_mov_b64_e32 v[86:87], v[4:5]
	v_mov_b64_e32 v[88:89], v[4:5]
	v_mov_b64_e32 v[90:91], v[4:5]
	v_mov_b64_e32 v[92:93], v[4:5]
	v_mov_b64_e32 v[94:95], v[4:5]
	v_mov_b64_e32 v[96:97], v[4:5]
	v_mov_b64_e32 v[98:99], v[4:5]
	v_mov_b64_e32 v[100:101], v[4:5]
	v_mov_b64_e32 v[102:103], v[4:5]
	v_mov_b64_e32 v[104:105], v[4:5]
	v_mov_b64_e32 v[106:107], v[4:5]
	v_mov_b64_e32 v[108:109], v[4:5]
	v_mov_b64_e32 v[110:111], v[4:5]
	v_mov_b64_e32 v[112:113], v[4:5]
	v_mov_b64_e32 v[114:115], v[4:5]
	v_mov_b64_e32 v[116:117], v[4:5]
	v_mov_b64_e32 v[118:119], v[4:5]
	v_mov_b64_e32 v[120:121], v[4:5]
	v_mov_b64_e32 v[122:123], v[4:5]
	v_mov_b64_e32 v[124:125], v[4:5]
	v_mov_b64_e32 v[126:127], v[4:5]
	v_mov_b64_e32 v[128:129], v[4:5]
	v_mov_b32_e32 v2, v4
	s_waitcnt vmcnt(0)
	s_barrier

.LBB0_1786:
	v_add_u32_e32 v155, s48, v153
	ds_read_b128 v[156:159], v155
	ds_read_b128 v[160:163], v155 offset:1024
	ds_read_b128 v[164:167], v155 offset:2048
	ds_read_b128 v[168:171], v155 offset:3072
	v_add_u32_e32 v155, s49, v153
	s_add_u32 s28, s10, s38
	ds_read_b128 v[172:175], v155
	ds_read_b128 v[176:179], v155 offset:1024
	ds_read_b128 v[180:183], v155 offset:2048
	ds_read_b128 v[184:187], v155 offset:3072
	s_addc_u32 s29, s11, s39
	s_add_u32 s28, s28, 0x100
	s_addc_u32 s29, s29, 0
	s_add_u32 s54, s21, s38
	s_addc_u32 s55, s50, s39
	s_cmpk_eq_i32 s38, 0x700
	s_cselect_b32 s31, s17, s29
	s_cselect_b32 s30, s51, s28
	s_cselect_b32 s29, s15, s55
	s_cselect_b32 s28, s52, s54
	v_lshl_add_u64 v[220:221], v[148:149], 0, s[38:39]
	s_add_i32 m0, s1, 0xc000
	ds_read_b128 v[188:191], v154
	ds_read_b128 v[192:195], v154 offset:1024
	ds_read_b128 v[196:199], v154 offset:2048
	ds_read_b128 v[200:203], v154 offset:3072
	ds_read_b128 v[204:207], v154 offset:4096
	ds_read_b128 v[208:211], v154 offset:5120
	ds_read_b128 v[212:215], v154 offset:6144
	ds_read_b128 v[216:219], v154 offset:7168
	global_load_lds_dwordx4 v[220:221], off
	v_lshl_add_u64 v[220:221], v[150:151], 0, s[38:39]
	s_add_i32 m0, s1, 0xe000
	s_nop 0
	global_load_lds_dwordx4 v[220:221], off
	s_waitcnt vmcnt(8)
	s_waitcnt lgkmcnt(0)
	s_barrier
	s_setprio 1
	s_waitcnt lgkmcnt(0)
	v_mfma_f32_16x16x32_bf16 v[126:129], v[156:159], v[188:191], v[126:129]
	v_mfma_f32_16x16x32_bf16 v[122:125], v[164:167], v[188:191], v[122:125]
	v_mfma_f32_16x16x32_bf16 v[110:113], v[156:159], v[196:199], v[110:113]
	v_mfma_f32_16x16x32_bf16 v[106:109], v[164:167], v[196:199], v[106:109]
	v_mfma_f32_16x16x32_bf16 v[94:97], v[156:159], v[204:207], v[94:97]
	v_mfma_f32_16x16x32_bf16 v[90:93], v[164:167], v[204:207], v[90:93]
	v_mfma_f32_16x16x32_bf16 v[78:81], v[156:159], v[212:215], v[78:81]
	v_mfma_f32_16x16x32_bf16 v[74:77], v[164:167], v[212:215], v[74:77]
	v_mfma_f32_16x16x32_bf16 v[126:129], v[160:163], v[192:195], v[126:129]
	v_mfma_f32_16x16x32_bf16 v[122:125], v[168:171], v[192:195], v[122:125]
	v_mfma_f32_16x16x32_bf16 v[110:113], v[160:163], v[200:203], v[110:113]
	v_mfma_f32_16x16x32_bf16 v[106:109], v[168:171], v[200:203], v[106:109]
	v_mfma_f32_16x16x32_bf16 v[94:97], v[160:163], v[208:211], v[94:97]
	v_mfma_f32_16x16x32_bf16 v[90:93], v[168:171], v[208:211], v[90:93]
	v_mfma_f32_16x16x32_bf16 v[78:81], v[160:163], v[216:219], v[78:81]
	v_mfma_f32_16x16x32_bf16 v[74:77], v[168:171], v[216:219], v[74:77]
	s_setprio 0
	s_setprio 1
	v_mfma_f32_16x16x32_bf16 v[118:121], v[172:175], v[188:191], v[118:121]
	v_mfma_f32_16x16x32_bf16 v[114:117], v[180:183], v[188:191], v[114:117]
	v_mfma_f32_16x16x32_bf16 v[102:105], v[172:175], v[196:199], v[102:105]
	v_mfma_f32_16x16x32_bf16 v[98:101], v[180:183], v[196:199], v[98:101]
	v_mfma_f32_16x16x32_bf16 v[86:89], v[172:175], v[204:207], v[86:89]
	v_mfma_f32_16x16x32_bf16 v[82:85], v[180:183], v[204:207], v[82:85]
	v_mfma_f32_16x16x32_bf16 v[70:73], v[172:175], v[212:215], v[70:73]
	v_mfma_f32_16x16x32_bf16 v[66:69], v[180:183], v[212:215], v[66:69]
	v_mfma_f32_16x16x32_bf16 v[118:121], v[176:179], v[192:195], v[118:121]
	v_mfma_f32_16x16x32_bf16 v[114:117], v[184:187], v[192:195], v[114:117]
	v_mfma_f32_16x16x32_bf16 v[102:105], v[176:179], v[200:203], v[102:105]
	v_mfma_f32_16x16x32_bf16 v[98:101], v[184:187], v[200:203], v[98:101]
	v_mfma_f32_16x16x32_bf16 v[86:89], v[176:179], v[208:211], v[86:89]
	v_mfma_f32_16x16x32_bf16 v[82:85], v[184:187], v[208:211], v[82:85]
	v_mfma_f32_16x16x32_bf16 v[70:73], v[176:179], v[216:219], v[70:73]
	v_mfma_f32_16x16x32_bf16 v[66:69], v[184:187], v[216:219], v[66:69]
	s_setprio 0
	s_barrier
	s_add_i32 s54, s48, s41
	s_mov_b32 m0, s54
	ds_read_b128 v[188:191], v154 offset:16384
	ds_read_b128 v[192:195], v154 offset:17408
	ds_read_b128 v[196:199], v154 offset:18432
	ds_read_b128 v[200:203], v154 offset:19456
	ds_read_b128 v[204:207], v154 offset:20480
	ds_read_b128 v[208:211], v154 offset:21504
	ds_read_b128 v[212:215], v154 offset:22528
	ds_read_b128 v[216:219], v154 offset:23552
	global_load_lds_dwordx4 v132, s[28:29]
	s_add_i32 m0, s54, 0x2000
	s_add_u32 s54, s28, 0x40000
	s_addc_u32 s55, s29, 0
	s_add_i32 s56, s49, s41
	global_load_lds_dwordx4 v136, s[28:29]
	s_mov_b32 m0, s56
	s_nop 0
	global_load_lds_dwordx4 v132, s[54:55]
	s_add_i32 m0, s56, 0x2000
	s_nop 0
	global_load_lds_dwordx4 v136, s[54:55]
	s_mov_b32 m0, s1
	s_nop 0
	global_load_lds_dwordx4 v130, s[30:31]
	s_mov_b32 m0, s42
	s_nop 0
	global_load_lds_dwordx4 v134, s[30:31]
	s_waitcnt vmcnt(8)
	s_waitcnt lgkmcnt(0)
	s_barrier
	s_setprio 1
	s_waitcnt lgkmcnt(0)
	v_mfma_f32_16x16x32_bf16 v[62:65], v[156:159], v[188:191], v[62:65]
	v_mfma_f32_16x16x32_bf16 v[58:61], v[164:167], v[188:191], v[58:61]
	v_mfma_f32_16x16x32_bf16 v[46:49], v[156:159], v[196:199], v[46:49]
	v_mfma_f32_16x16x32_bf16 v[42:45], v[164:167], v[196:199], v[42:45]
	v_mfma_f32_16x16x32_bf16 v[30:33], v[156:159], v[204:207], v[30:33]
	v_mfma_f32_16x16x32_bf16 v[26:29], v[164:167], v[204:207], v[26:29]
	v_mfma_f32_16x16x32_bf16 v[14:17], v[156:159], v[212:215], v[14:17]
	v_mfma_f32_16x16x32_bf16 v[10:13], v[164:167], v[212:215], v[10:13]
	v_mfma_f32_16x16x32_bf16 v[62:65], v[160:163], v[192:195], v[62:65]
	v_mfma_f32_16x16x32_bf16 v[58:61], v[168:171], v[192:195], v[58:61]
	v_mfma_f32_16x16x32_bf16 v[46:49], v[160:163], v[200:203], v[46:49]
	v_mfma_f32_16x16x32_bf16 v[42:45], v[168:171], v[200:203], v[42:45]
	v_mfma_f32_16x16x32_bf16 v[30:33], v[160:163], v[208:211], v[30:33]
	v_mfma_f32_16x16x32_bf16 v[26:29], v[168:171], v[208:211], v[26:29]
	v_mfma_f32_16x16x32_bf16 v[14:17], v[160:163], v[216:219], v[14:17]
	v_mfma_f32_16x16x32_bf16 v[10:13], v[168:171], v[216:219], v[10:13]
	s_setprio 0
	s_setprio 1
	v_mfma_f32_16x16x32_bf16 v[54:57], v[172:175], v[188:191], v[54:57]
	v_mfma_f32_16x16x32_bf16 v[50:53], v[180:183], v[188:191], v[50:53]
	v_mfma_f32_16x16x32_bf16 v[38:41], v[172:175], v[196:199], v[38:41]
	v_mfma_f32_16x16x32_bf16 v[34:37], v[180:183], v[196:199], v[34:37]
	v_mfma_f32_16x16x32_bf16 v[22:25], v[172:175], v[204:207], v[22:25]
	v_mfma_f32_16x16x32_bf16 v[18:21], v[180:183], v[204:207], v[18:21]
	v_mfma_f32_16x16x32_bf16 v[6:9], v[172:175], v[212:215], v[6:9]
	v_mfma_f32_16x16x32_bf16 v[2:5], v[180:183], v[212:215], v[2:5]
	v_mfma_f32_16x16x32_bf16 v[54:57], v[176:179], v[192:195], v[54:57]
	v_mfma_f32_16x16x32_bf16 v[50:53], v[184:187], v[192:195], v[50:53]
	v_mfma_f32_16x16x32_bf16 v[38:41], v[176:179], v[200:203], v[38:41]
	v_mfma_f32_16x16x32_bf16 v[34:37], v[184:187], v[200:203], v[34:37]
	v_mfma_f32_16x16x32_bf16 v[22:25], v[176:179], v[208:211], v[22:25]
	v_mfma_f32_16x16x32_bf16 v[18:21], v[184:187], v[208:211], v[18:21]
	v_mfma_f32_16x16x32_bf16 v[6:9], v[176:179], v[216:219], v[6:9]
	v_mfma_f32_16x16x32_bf16 v[2:5], v[184:187], v[216:219], v[2:5]
	s_setprio 0
	s_barrier
	s_add_i32 s54, 0, 0x18000
	v_add_u32_e32 v155, s54, v153
	s_add_i32 s55, 0, 0x1c000
	ds_read_b128 v[156:159], v155
	ds_read_b128 v[160:163], v155 offset:1024
	ds_read_b128 v[164:167], v155 offset:2048
	ds_read_b128 v[168:171], v155 offset:3072
	v_add_u32_e32 v155, s55, v153
	ds_read_b128 v[172:175], v155
	ds_read_b128 v[176:179], v155 offset:1024
	ds_read_b128 v[180:183], v155 offset:2048
	ds_read_b128 v[184:187], v155 offset:3072
	s_add_u32 s98, s30, 0x40000
	s_addc_u32 s99, s31, 0
	s_mov_b32 m0, s43
	ds_read_b128 v[188:191], v154 offset:32768
	ds_read_b128 v[192:195], v154 offset:33792
	ds_read_b128 v[196:199], v154 offset:34816
	ds_read_b128 v[200:203], v154 offset:35840
	ds_read_b128 v[204:207], v154 offset:36864
	ds_read_b128 v[208:211], v154 offset:37888
	ds_read_b128 v[212:215], v154 offset:38912
	ds_read_b128 v[216:219], v154 offset:39936
	global_load_lds_dwordx4 v130, s[98:99]
	s_mov_b32 m0, s44
	s_nop 0
	global_load_lds_dwordx4 v134, s[98:99]
	s_waitcnt vmcnt(8)
	s_waitcnt lgkmcnt(0)
	s_barrier
	s_setprio 1
	s_waitcnt lgkmcnt(0)
	v_mfma_f32_16x16x32_bf16 v[126:129], v[156:159], v[188:191], v[126:129]
	v_mfma_f32_16x16x32_bf16 v[122:125], v[164:167], v[188:191], v[122:125]
	v_mfma_f32_16x16x32_bf16 v[110:113], v[156:159], v[196:199], v[110:113]
	v_mfma_f32_16x16x32_bf16 v[106:109], v[164:167], v[196:199], v[106:109]
	v_mfma_f32_16x16x32_bf16 v[94:97], v[156:159], v[204:207], v[94:97]
	v_mfma_f32_16x16x32_bf16 v[90:93], v[164:167], v[204:207], v[90:93]
	v_mfma_f32_16x16x32_bf16 v[78:81], v[156:159], v[212:215], v[78:81]
	v_mfma_f32_16x16x32_bf16 v[74:77], v[164:167], v[212:215], v[74:77]
	v_mfma_f32_16x16x32_bf16 v[126:129], v[160:163], v[192:195], v[126:129]
	v_mfma_f32_16x16x32_bf16 v[122:125], v[168:171], v[192:195], v[122:125]
	v_mfma_f32_16x16x32_bf16 v[110:113], v[160:163], v[200:203], v[110:113]
	v_mfma_f32_16x16x32_bf16 v[106:109], v[168:171], v[200:203], v[106:109]
	v_mfma_f32_16x16x32_bf16 v[94:97], v[160:163], v[208:211], v[94:97]
	v_mfma_f32_16x16x32_bf16 v[90:93], v[168:171], v[208:211], v[90:93]
	v_mfma_f32_16x16x32_bf16 v[78:81], v[160:163], v[216:219], v[78:81]
	v_mfma_f32_16x16x32_bf16 v[74:77], v[168:171], v[216:219], v[74:77]
	s_setprio 0
	s_setprio 1
	v_mfma_f32_16x16x32_bf16 v[118:121], v[172:175], v[188:191], v[118:121]
	v_mfma_f32_16x16x32_bf16 v[114:117], v[180:183], v[188:191], v[114:117]
	v_mfma_f32_16x16x32_bf16 v[102:105], v[172:175], v[196:199], v[102:105]
	v_mfma_f32_16x16x32_bf16 v[98:101], v[180:183], v[196:199], v[98:101]
	v_mfma_f32_16x16x32_bf16 v[86:89], v[172:175], v[204:207], v[86:89]
	v_mfma_f32_16x16x32_bf16 v[82:85], v[180:183], v[204:207], v[82:85]
	v_mfma_f32_16x16x32_bf16 v[70:73], v[172:175], v[212:215], v[70:73]
	v_mfma_f32_16x16x32_bf16 v[66:69], v[180:183], v[212:215], v[66:69]
	v_mfma_f32_16x16x32_bf16 v[118:121], v[176:179], v[192:195], v[118:121]
	v_mfma_f32_16x16x32_bf16 v[114:117], v[184:187], v[192:195], v[114:117]
	v_mfma_f32_16x16x32_bf16 v[102:105], v[176:179], v[200:203], v[102:105]
	v_mfma_f32_16x16x32_bf16 v[98:101], v[184:187], v[200:203], v[98:101]
	v_mfma_f32_16x16x32_bf16 v[86:89], v[176:179], v[208:211], v[86:89]
	v_mfma_f32_16x16x32_bf16 v[82:85], v[184:187], v[208:211], v[82:85]
	v_mfma_f32_16x16x32_bf16 v[70:73], v[176:179], v[216:219], v[70:73]
	v_mfma_f32_16x16x32_bf16 v[66:69], v[184:187], v[216:219], v[66:69]
	s_setprio 0
	s_barrier
	s_add_i32 s98, s54, s41
	s_add_i32 m0, s98, 0xffffff80
	ds_read_b128 v[188:191], v154 offset:49152
	ds_read_b128 v[192:195], v154 offset:50176
	ds_read_b128 v[196:199], v154 offset:51200
	ds_read_b128 v[200:203], v154 offset:52224
	ds_read_b128 v[204:207], v154 offset:53248
	ds_read_b128 v[208:211], v154 offset:54272
	ds_read_b128 v[212:215], v154 offset:55296
	ds_read_b128 v[216:219], v154 offset:56320
	global_load_lds_dwordx4 v132, s[28:29] offset:128
	s_add_i32 m0, s98, 0x1f80
	s_add_i32 s98, s55, s41
	global_load_lds_dwordx4 v136, s[28:29] offset:128
	s_add_u32 s28, s28, 0x40080
	s_addc_u32 s29, s29, 0
	s_mov_b32 m0, s98
	s_nop 0
	global_load_lds_dwordx4 v132, s[28:29]
	s_add_i32 m0, s98, 0x2000
	s_nop 0
	global_load_lds_dwordx4 v136, s[28:29]
	s_add_i32 m0, s46, 0xffffff80
	s_nop 0
	global_load_lds_dwordx4 v130, s[30:31] offset:128
	s_add_i32 m0, s47, 0xffffff80
	s_nop 0
	global_load_lds_dwordx4 v134, s[30:31] offset:128
	s_waitcnt vmcnt(8)
	s_waitcnt lgkmcnt(0)
	s_barrier
	s_setprio 1
	s_waitcnt lgkmcnt(0)
	v_mfma_f32_16x16x32_bf16 v[62:65], v[156:159], v[188:191], v[62:65]
	v_mfma_f32_16x16x32_bf16 v[58:61], v[164:167], v[188:191], v[58:61]
	v_mfma_f32_16x16x32_bf16 v[46:49], v[156:159], v[196:199], v[46:49]
	v_mfma_f32_16x16x32_bf16 v[42:45], v[164:167], v[196:199], v[42:45]
	v_mfma_f32_16x16x32_bf16 v[30:33], v[156:159], v[204:207], v[30:33]
	v_mfma_f32_16x16x32_bf16 v[26:29], v[164:167], v[204:207], v[26:29]
	v_mfma_f32_16x16x32_bf16 v[14:17], v[156:159], v[212:215], v[14:17]
	v_mfma_f32_16x16x32_bf16 v[10:13], v[164:167], v[212:215], v[10:13]
	v_mfma_f32_16x16x32_bf16 v[62:65], v[160:163], v[192:195], v[62:65]
	v_mfma_f32_16x16x32_bf16 v[58:61], v[168:171], v[192:195], v[58:61]
	v_mfma_f32_16x16x32_bf16 v[46:49], v[160:163], v[200:203], v[46:49]
	v_mfma_f32_16x16x32_bf16 v[42:45], v[168:171], v[200:203], v[42:45]
	v_mfma_f32_16x16x32_bf16 v[30:33], v[160:163], v[208:211], v[30:33]
	v_mfma_f32_16x16x32_bf16 v[26:29], v[168:171], v[208:211], v[26:29]
	v_mfma_f32_16x16x32_bf16 v[14:17], v[160:163], v[216:219], v[14:17]
	v_mfma_f32_16x16x32_bf16 v[10:13], v[168:171], v[216:219], v[10:13]
	s_setprio 0
	s_setprio 1
	v_mfma_f32_16x16x32_bf16 v[54:57], v[172:175], v[188:191], v[54:57]
	v_mfma_f32_16x16x32_bf16 v[50:53], v[180:183], v[188:191], v[50:53]
	v_mfma_f32_16x16x32_bf16 v[38:41], v[172:175], v[196:199], v[38:41]
	v_mfma_f32_16x16x32_bf16 v[34:37], v[180:183], v[196:199], v[34:37]
	v_mfma_f32_16x16x32_bf16 v[22:25], v[172:175], v[204:207], v[22:25]
	v_mfma_f32_16x16x32_bf16 v[18:21], v[180:183], v[204:207], v[18:21]
	v_mfma_f32_16x16x32_bf16 v[6:9], v[172:175], v[212:215], v[6:9]
	v_mfma_f32_16x16x32_bf16 v[2:5], v[180:183], v[212:215], v[2:5]
	v_mfma_f32_16x16x32_bf16 v[54:57], v[176:179], v[192:195], v[54:57]
	v_mfma_f32_16x16x32_bf16 v[50:53], v[184:187], v[192:195], v[50:53]
	v_mfma_f32_16x16x32_bf16 v[38:41], v[176:179], v[200:203], v[38:41]
	v_mfma_f32_16x16x32_bf16 v[34:37], v[184:187], v[200:203], v[34:37]
	v_mfma_f32_16x16x32_bf16 v[22:25], v[176:179], v[208:211], v[22:25]
	v_mfma_f32_16x16x32_bf16 v[18:21], v[184:187], v[208:211], v[18:21]
	v_mfma_f32_16x16x32_bf16 v[6:9], v[176:179], v[216:219], v[6:9]
	v_mfma_f32_16x16x32_bf16 v[2:5], v[184:187], v[216:219], v[2:5]
	s_setprio 0
	s_barrier
	s_add_i32 s53, s53, 2
	s_add_u32 s38, s38, 0x100
	s_addc_u32 s39, s39, 0
	s_cmp_gt_u32 s53, 13
	s_cbranch_scc0 .LBB0_1786
	s_add_u32 s28, s21, 0xffffff00
	s_addc_u32 s29, s50, -1
	s_andn2_b64 vcc, exec, s[4:5]
	s_cbranch_vccnz .LBB0_1789
	v_mov_b32_e32 v2, 0
	v_mov_b32_e32 v3, 0
	v_mov_b64_e32 v[4:5], v[2:3]
	v_mov_b64_e32 v[6:7], v[2:3]
	v_mov_b64_e32 v[8:9], v[2:3]
	v_mov_b64_e32 v[10:11], v[2:3]
	v_mov_b64_e32 v[12:13], v[2:3]
	v_mov_b64_e32 v[14:15], v[2:3]
	v_mov_b64_e32 v[16:17], v[2:3]
	v_mov_b64_e32 v[18:19], v[2:3]
	v_mov_b64_e32 v[20:21], v[2:3]
	v_mov_b64_e32 v[22:23], v[2:3]
	v_mov_b64_e32 v[24:25], v[2:3]
	v_mov_b64_e32 v[26:27], v[2:3]
	v_mov_b64_e32 v[28:29], v[2:3]
	v_mov_b64_e32 v[30:31], v[2:3]
	v_mov_b64_e32 v[32:33], v[2:3]
	v_mov_b64_e32 v[34:35], v[2:3]
	v_mov_b64_e32 v[36:37], v[2:3]
	v_mov_b64_e32 v[38:39], v[2:3]
	v_mov_b64_e32 v[40:41], v[2:3]
	v_mov_b64_e32 v[42:43], v[2:3]
	v_mov_b64_e32 v[44:45], v[2:3]
	v_mov_b64_e32 v[46:47], v[2:3]
	v_mov_b64_e32 v[48:49], v[2:3]
	v_mov_b64_e32 v[50:51], v[2:3]
	v_mov_b64_e32 v[52:53], v[2:3]
	v_mov_b64_e32 v[54:55], v[2:3]
	v_mov_b64_e32 v[56:57], v[2:3]
	v_mov_b64_e32 v[58:59], v[2:3]
	v_mov_b64_e32 v[60:61], v[2:3]
	v_mov_b64_e32 v[62:63], v[2:3]
	v_mov_b64_e32 v[64:65], v[2:3]
	v_mov_b64_e32 v[66:67], v[2:3]
	v_mov_b64_e32 v[68:69], v[2:3]
	v_mov_b64_e32 v[70:71], v[2:3]
	v_mov_b64_e32 v[72:73], v[2:3]
	v_mov_b64_e32 v[74:75], v[2:3]
	v_mov_b64_e32 v[76:77], v[2:3]
	v_mov_b64_e32 v[78:79], v[2:3]
	v_mov_b64_e32 v[80:81], v[2:3]
	v_mov_b64_e32 v[82:83], v[2:3]
	v_mov_b64_e32 v[84:85], v[2:3]
	v_mov_b64_e32 v[86:87], v[2:3]
	v_mov_b64_e32 v[88:89], v[2:3]
	v_mov_b64_e32 v[90:91], v[2:3]
	v_mov_b64_e32 v[92:93], v[2:3]
	v_mov_b64_e32 v[94:95], v[2:3]
	v_mov_b64_e32 v[96:97], v[2:3]
	v_mov_b64_e32 v[98:99], v[2:3]
	v_mov_b64_e32 v[100:101], v[2:3]
	v_mov_b64_e32 v[102:103], v[2:3]
	v_mov_b64_e32 v[104:105], v[2:3]
	v_mov_b64_e32 v[106:107], v[2:3]
	v_mov_b64_e32 v[108:109], v[2:3]
	v_mov_b64_e32 v[110:111], v[2:3]
	v_mov_b64_e32 v[112:113], v[2:3]
	v_mov_b64_e32 v[114:115], v[2:3]
	v_mov_b64_e32 v[116:117], v[2:3]
	v_mov_b64_e32 v[118:119], v[2:3]
	v_mov_b64_e32 v[120:121], v[2:3]
	v_mov_b64_e32 v[122:123], v[2:3]
	v_mov_b64_e32 v[124:125], v[2:3]
	v_mov_b64_e32 v[126:127], v[2:3]
	v_mov_b64_e32 v[128:129], v[2:3]
	s_mov_b32 s6, s14
	s_mov_b32 s0, s16
	s_mov_b64 s[10:11], s[36:37]
	s_mov_b32 s45, s20
	s_andn2_b64 vcc, exec, s[2:3]
	s_cbranch_vccnz .LBB0_1790
	s_branch .LBB0_1791

.LBB0_1904:
	s_ashr_i32 s51, s50, 31
	s_lshl_b64 s[52:53], s[50:51], 19
	s_add_u32 s52, s80, s52
	s_addc_u32 s53, s81, s53
	s_and_b64 s[54:55], s[4:5], exec
	s_cselect_b32 s51, s53, s31
	s_cselect_b32 s60, s52, s30
	s_ashr_i32 s49, s48, 31
	s_lshl_b64 s[54:55], s[48:49], 19
	s_add_u32 s54, s24, s54
	s_addc_u32 s55, s25, s55
	s_and_b64 s[58:59], s[4:5], exec
	s_cselect_b32 s49, s55, s29
	s_cselect_b32 s61, s54, s28
	s_add_u32 s58, s30, 0x40080
	s_addc_u32 s59, s31, 0
	s_add_u32 s72, s28, 0x100
	v_mov_b32_e32 v2, 0
	v_mov_b32_e32 v3, 0
	v_mov_b64_e32 v[4:5], v[2:3]
	v_mov_b64_e32 v[6:7], v[2:3]
	v_mov_b64_e32 v[8:9], v[2:3]
	v_mov_b64_e32 v[10:11], v[2:3]
	v_mov_b64_e32 v[12:13], v[2:3]
	v_mov_b64_e32 v[14:15], v[2:3]
	v_mov_b64_e32 v[16:17], v[2:3]
	v_mov_b64_e32 v[18:19], v[2:3]
	v_mov_b64_e32 v[20:21], v[2:3]
	v_mov_b64_e32 v[22:23], v[2:3]
	v_mov_b64_e32 v[24:25], v[2:3]
	v_mov_b64_e32 v[26:27], v[2:3]
	v_mov_b64_e32 v[28:29], v[2:3]
	v_mov_b64_e32 v[30:31], v[2:3]
	v_mov_b64_e32 v[32:33], v[2:3]
	v_mov_b64_e32 v[34:35], v[2:3]
	v_mov_b64_e32 v[36:37], v[2:3]
	v_mov_b64_e32 v[38:39], v[2:3]
	v_mov_b64_e32 v[40:41], v[2:3]
	v_mov_b64_e32 v[42:43], v[2:3]
	v_mov_b64_e32 v[44:45], v[2:3]
	v_mov_b64_e32 v[46:47], v[2:3]
	v_mov_b64_e32 v[48:49], v[2:3]
	v_mov_b64_e32 v[50:51], v[2:3]
	v_mov_b64_e32 v[52:53], v[2:3]
	v_mov_b64_e32 v[54:55], v[2:3]
	v_mov_b64_e32 v[56:57], v[2:3]
	v_mov_b64_e32 v[58:59], v[2:3]
	v_mov_b64_e32 v[60:61], v[2:3]
	v_mov_b64_e32 v[62:63], v[2:3]
	v_mov_b64_e32 v[64:65], v[2:3]
	v_mov_b64_e32 v[66:67], v[2:3]
	v_mov_b64_e32 v[68:69], v[2:3]
	v_mov_b64_e32 v[70:71], v[2:3]
	v_mov_b64_e32 v[72:73], v[2:3]
	v_mov_b64_e32 v[74:75], v[2:3]
	v_mov_b64_e32 v[76:77], v[2:3]
	v_mov_b64_e32 v[78:79], v[2:3]
	v_mov_b64_e32 v[80:81], v[2:3]
	v_mov_b64_e32 v[82:83], v[2:3]
	v_mov_b64_e32 v[84:85], v[2:3]
	v_mov_b64_e32 v[86:87], v[2:3]
	v_mov_b64_e32 v[88:89], v[2:3]
	v_mov_b64_e32 v[90:91], v[2:3]
	v_mov_b64_e32 v[92:93], v[2:3]
	v_mov_b64_e32 v[94:95], v[2:3]
	v_mov_b64_e32 v[96:97], v[2:3]
	v_mov_b64_e32 v[98:99], v[2:3]
	v_mov_b64_e32 v[100:101], v[2:3]
	v_mov_b64_e32 v[102:103], v[2:3]
	v_mov_b64_e32 v[104:105], v[2:3]
	v_mov_b64_e32 v[106:107], v[2:3]
	v_mov_b64_e32 v[108:109], v[2:3]
	v_mov_b64_e32 v[110:111], v[2:3]
	v_mov_b64_e32 v[112:113], v[2:3]
	v_mov_b64_e32 v[114:115], v[2:3]
	v_mov_b64_e32 v[116:117], v[2:3]
	v_mov_b64_e32 v[118:119], v[2:3]
	v_mov_b64_e32 v[120:121], v[2:3]
	v_mov_b64_e32 v[122:123], v[2:3]
	v_mov_b64_e32 v[124:125], v[2:3]
	v_mov_b64_e32 v[126:127], v[2:3]
	v_mov_b64_e32 v[128:129], v[2:3]
	s_addc_u32 s73, s29, 0
	s_mov_b32 s74, -2
	s_waitcnt vmcnt(0)

.LBB0_2019:
	v_and_b32_e32 v139, 15, v0
	v_and_b32_e32 v14, 48, v0
	v_lshlrev_b32_e32 v16, 2, v0
	s_sext_i32_i8 s10, s0
	v_lshl_or_b32 v15, v139, 6, v14
	s_lshl_b32 s0, s24, 13
	v_and_b32_e32 v16, 32, v16
	s_mov_b64 s[14:15], 0x80
	s_and_b32 s25, s11, 3
	v_bitop3_b32 v15, v15, s0, v16 bitop3:0xde
	v_lshlrev_b32_e32 v17, 6, v0
	s_movk_i32 s0, 0x3c0
	s_add_i32 m0, s41, 0x18000
	v_lshl_add_u64 v[8:9], v[8:9], 0, s[14:15]
	v_and_or_b32 v14, v17, s0, v14
	s_lshl_b32 s0, s25, 12
	s_waitcnt vmcnt(2)
	s_barrier
	global_load_lds_dwordx4 v[8:9], off
	v_lshl_add_u64 v[6:7], v[6:7], 0, s[14:15]
	s_add_i32 m0, s41, 0x1a000
	s_add_i32 s46, s41, 0x8000
	s_add_i32 s47, s41, 0xa000
	global_load_lds_dwordx4 v[6:7], off
	v_lshl_add_u64 v[4:5], v[4:5], 0, s[14:15]
	s_mov_b32 m0, s46
	s_add_u32 s2, s20, 0xb0080
	global_load_lds_dwordx4 v[4:5], off
	v_lshl_add_u64 v[2:3], v[2:3], 0, s[14:15]
	s_mov_b32 m0, s47
	s_addc_u32 s3, s21, 0
	global_load_lds_dwordx4 v[2:3], off
	s_add_i32 m0, s41, 0x1c000
	v_lshl_add_u64 v[2:3], s[2:3], 0, v[132:133]
	global_load_lds_dwordx4 v[2:3], off
	v_lshl_add_u64 v[2:3], s[2:3], 0, v[136:137]
	s_add_i32 m0, s41, 0x1e000
	v_bitop3_b32 v153, s0, v14, v16 bitop3:0xf6
	global_load_lds_dwordx4 v[2:3], off
	v_add_u16_e32 v2, v10, v11
	v_lshrrev_b16_e32 v4, 1, v2
	s_mov_b64 s[0:1], 0xb0080
	s_waitcnt vmcnt(6)
	v_add_lshl_u32 v2, v12, v4, 1
	v_mov_b32_e32 v3, v133
	v_lshl_add_u64 v[140:141], v[2:3], 0, s[0:1]
	v_add_lshl_u32 v2, v13, v4, 1
	v_lshl_or_b32 v1, s24, 6, v139
	v_lshl_add_u64 v[142:143], v[2:3], 0, s[0:1]
	v_mov_b64_e32 v[144:145], 0x100
	v_mov_b64_e32 v[146:147], 0xff
	s_add_i32 s48, 0, 0x10000
	s_add_i32 s49, 0, 0x14000
	v_add_u32_e32 v154, 0, v15
	v_mov_b32_e32 v4, v133
	v_mov_b32_e32 v5, v133
	v_mov_b64_e32 v[6:7], v[4:5]
	v_mov_b64_e32 v[8:9], v[4:5]
	v_mov_b64_e32 v[10:11], v[4:5]
	v_mov_b64_e32 v[12:13], v[4:5]
	v_mov_b64_e32 v[14:15], v[4:5]
	v_mov_b64_e32 v[16:17], v[4:5]
	v_mov_b64_e32 v[18:19], v[4:5]
	v_mov_b64_e32 v[20:21], v[4:5]
	v_mov_b64_e32 v[22:23], v[4:5]
	v_mov_b64_e32 v[24:25], v[4:5]
	v_mov_b64_e32 v[26:27], v[4:5]
	v_mov_b64_e32 v[28:29], v[4:5]
	v_mov_b64_e32 v[30:31], v[4:5]
	v_mov_b64_e32 v[32:33], v[4:5]
	v_mov_b64_e32 v[34:35], v[4:5]
	v_mov_b64_e32 v[36:37], v[4:5]
	v_mov_b64_e32 v[38:39], v[4:5]
	v_mov_b64_e32 v[40:41], v[4:5]
	v_mov_b64_e32 v[42:43], v[4:5]
	v_mov_b64_e32 v[44:45], v[4:5]
	v_mov_b64_e32 v[46:47], v[4:5]
	v_mov_b64_e32 v[48:49], v[4:5]
	v_mov_b64_e32 v[50:51], v[4:5]
	v_mov_b64_e32 v[52:53], v[4:5]
	v_mov_b64_e32 v[54:55], v[4:5]
	v_mov_b64_e32 v[56:57], v[4:5]
	v_mov_b64_e32 v[58:59], v[4:5]
	v_mov_b64_e32 v[60:61], v[4:5]
	v_mov_b64_e32 v[62:63], v[4:5]
	v_mov_b64_e32 v[64:65], v[4:5]
	v_mov_b64_e32 v[66:67], v[4:5]
	v_mov_b64_e32 v[68:69], v[4:5]
	v_mov_b64_e32 v[70:71], v[4:5]
	v_mov_b64_e32 v[72:73], v[4:5]
	v_mov_b64_e32 v[74:75], v[4:5]
	v_mov_b64_e32 v[76:77], v[4:5]
	v_mov_b64_e32 v[78:79], v[4:5]
	v_mov_b64_e32 v[80:81], v[4:5]
	v_mov_b64_e32 v[82:83], v[4:5]
	v_mov_b64_e32 v[84:85], v[4:5]
	v_mov_b64_e32 v[86:87], v[4:5]
	v_mov_b64_e32 v[88:89], v[4:5]
	v_mov_b64_e32 v[90:91], v[4:5]
	v_mov_b64_e32 v[92:93], v[4:5]
	v_mov_b64_e32 v[94:95], v[4:5]
	v_mov_b64_e32 v[96:97], v[4:5]
	v_mov_b64_e32 v[98:99], v[4:5]
	v_mov_b64_e32 v[100:101], v[4:5]
	v_mov_b64_e32 v[102:103], v[4:5]
	v_mov_b64_e32 v[104:105], v[4:5]
	v_mov_b64_e32 v[106:107], v[4:5]
	v_mov_b64_e32 v[108:109], v[4:5]
	v_mov_b64_e32 v[110:111], v[4:5]
	v_mov_b64_e32 v[112:113], v[4:5]
	v_mov_b64_e32 v[114:115], v[4:5]
	v_mov_b64_e32 v[116:117], v[4:5]
	v_mov_b64_e32 v[118:119], v[4:5]
	v_mov_b64_e32 v[120:121], v[4:5]
	v_mov_b64_e32 v[122:123], v[4:5]
	v_mov_b64_e32 v[124:125], v[4:5]
	v_mov_b64_e32 v[126:127], v[4:5]
	v_mov_b64_e32 v[128:129], v[4:5]
	v_mov_b32_e32 v2, v4
	s_waitcnt vmcnt(0)
	s_barrier

.LBB0_2031:
	v_add_u32_e32 v155, s48, v153
	ds_read_b128 v[156:159], v155
	ds_read_b128 v[160:163], v155 offset:1024
	ds_read_b128 v[164:167], v155 offset:2048
	ds_read_b128 v[168:171], v155 offset:3072
	v_add_u32_e32 v155, s49, v153
	s_add_u32 s28, s12, s20
	ds_read_b128 v[172:175], v155
	ds_read_b128 v[176:179], v155 offset:1024
	ds_read_b128 v[180:183], v155 offset:2048
	ds_read_b128 v[184:187], v155 offset:3072
	s_addc_u32 s29, s13, s21
	s_add_u32 s28, s28, 0x100
	s_addc_u32 s29, s29, 0
	s_add_u32 s54, s17, s20
	s_addc_u32 s55, s52, s21
	s_cmpk_eq_i32 s20, 0x1500
	s_cselect_b32 s31, s19, s29
	s_cselect_b32 s30, s18, s28
	s_cselect_b32 s29, s1, s55
	s_cselect_b32 s28, s0, s54
	v_lshl_add_u64 v[220:221], v[148:149], 0, s[20:21]
	s_add_i32 m0, s41, 0xc000
	ds_read_b128 v[188:191], v154
	ds_read_b128 v[192:195], v154 offset:1024
	ds_read_b128 v[196:199], v154 offset:2048
	ds_read_b128 v[200:203], v154 offset:3072
	ds_read_b128 v[204:207], v154 offset:4096
	ds_read_b128 v[208:211], v154 offset:5120
	ds_read_b128 v[212:215], v154 offset:6144
	ds_read_b128 v[216:219], v154 offset:7168
	global_load_lds_dwordx4 v[220:221], off
	v_lshl_add_u64 v[220:221], v[150:151], 0, s[20:21]
	s_add_i32 m0, s41, 0xe000
	s_nop 0
	global_load_lds_dwordx4 v[220:221], off
	s_waitcnt vmcnt(8)
	s_waitcnt lgkmcnt(0)
	s_barrier
	s_setprio 1
	s_waitcnt lgkmcnt(0)
	v_mfma_f32_16x16x32_bf16 v[126:129], v[156:159], v[188:191], v[126:129]
	v_mfma_f32_16x16x32_bf16 v[122:125], v[164:167], v[188:191], v[122:125]
	v_mfma_f32_16x16x32_bf16 v[110:113], v[156:159], v[196:199], v[110:113]
	v_mfma_f32_16x16x32_bf16 v[106:109], v[164:167], v[196:199], v[106:109]
	v_mfma_f32_16x16x32_bf16 v[94:97], v[156:159], v[204:207], v[94:97]
	v_mfma_f32_16x16x32_bf16 v[90:93], v[164:167], v[204:207], v[90:93]
	v_mfma_f32_16x16x32_bf16 v[78:81], v[156:159], v[212:215], v[78:81]
	v_mfma_f32_16x16x32_bf16 v[74:77], v[164:167], v[212:215], v[74:77]
	v_mfma_f32_16x16x32_bf16 v[126:129], v[160:163], v[192:195], v[126:129]
	v_mfma_f32_16x16x32_bf16 v[122:125], v[168:171], v[192:195], v[122:125]
	v_mfma_f32_16x16x32_bf16 v[110:113], v[160:163], v[200:203], v[110:113]
	v_mfma_f32_16x16x32_bf16 v[106:109], v[168:171], v[200:203], v[106:109]
	v_mfma_f32_16x16x32_bf16 v[94:97], v[160:163], v[208:211], v[94:97]
	v_mfma_f32_16x16x32_bf16 v[90:93], v[168:171], v[208:211], v[90:93]
	v_mfma_f32_16x16x32_bf16 v[78:81], v[160:163], v[216:219], v[78:81]
	v_mfma_f32_16x16x32_bf16 v[74:77], v[168:171], v[216:219], v[74:77]
	s_setprio 0
	s_setprio 1
	v_mfma_f32_16x16x32_bf16 v[118:121], v[172:175], v[188:191], v[118:121]
	v_mfma_f32_16x16x32_bf16 v[114:117], v[180:183], v[188:191], v[114:117]
	v_mfma_f32_16x16x32_bf16 v[102:105], v[172:175], v[196:199], v[102:105]
	v_mfma_f32_16x16x32_bf16 v[98:101], v[180:183], v[196:199], v[98:101]
	v_mfma_f32_16x16x32_bf16 v[86:89], v[172:175], v[204:207], v[86:89]
	v_mfma_f32_16x16x32_bf16 v[82:85], v[180:183], v[204:207], v[82:85]
	v_mfma_f32_16x16x32_bf16 v[70:73], v[172:175], v[212:215], v[70:73]
	v_mfma_f32_16x16x32_bf16 v[66:69], v[180:183], v[212:215], v[66:69]
	v_mfma_f32_16x16x32_bf16 v[118:121], v[176:179], v[192:195], v[118:121]
	v_mfma_f32_16x16x32_bf16 v[114:117], v[184:187], v[192:195], v[114:117]
	v_mfma_f32_16x16x32_bf16 v[102:105], v[176:179], v[200:203], v[102:105]
	v_mfma_f32_16x16x32_bf16 v[98:101], v[184:187], v[200:203], v[98:101]
	v_mfma_f32_16x16x32_bf16 v[86:89], v[176:179], v[208:211], v[86:89]
	v_mfma_f32_16x16x32_bf16 v[82:85], v[184:187], v[208:211], v[82:85]
	v_mfma_f32_16x16x32_bf16 v[70:73], v[176:179], v[216:219], v[70:73]
	v_mfma_f32_16x16x32_bf16 v[66:69], v[184:187], v[216:219], v[66:69]
	s_setprio 0
	s_barrier
	s_add_i32 s54, s48, s35
	s_mov_b32 m0, s54
	ds_read_b128 v[188:191], v154 offset:16384
	ds_read_b128 v[192:195], v154 offset:17408
	ds_read_b128 v[196:199], v154 offset:18432
	ds_read_b128 v[200:203], v154 offset:19456
	ds_read_b128 v[204:207], v154 offset:20480
	ds_read_b128 v[208:211], v154 offset:21504
	ds_read_b128 v[212:215], v154 offset:22528
	ds_read_b128 v[216:219], v154 offset:23552
	global_load_lds_dwordx4 v132, s[28:29]
	s_add_i32 m0, s54, 0x2000
	s_add_u32 s54, s28, 0xb0000
	s_addc_u32 s55, s29, 0
	s_add_i32 s56, s49, s35
	global_load_lds_dwordx4 v136, s[28:29]
	s_mov_b32 m0, s56
	s_nop 0
	global_load_lds_dwordx4 v132, s[54:55]
	s_add_i32 m0, s56, 0x2000
	s_nop 0
	global_load_lds_dwordx4 v136, s[54:55]
	s_mov_b32 m0, s41
	s_nop 0
	global_load_lds_dwordx4 v130, s[30:31]
	s_mov_b32 m0, s42
	s_nop 0
	global_load_lds_dwordx4 v134, s[30:31]
	s_waitcnt vmcnt(8)
	s_waitcnt lgkmcnt(0)
	s_barrier
	s_setprio 1
	s_waitcnt lgkmcnt(0)
	v_mfma_f32_16x16x32_bf16 v[62:65], v[156:159], v[188:191], v[62:65]
	v_mfma_f32_16x16x32_bf16 v[58:61], v[164:167], v[188:191], v[58:61]
	v_mfma_f32_16x16x32_bf16 v[46:49], v[156:159], v[196:199], v[46:49]
	v_mfma_f32_16x16x32_bf16 v[42:45], v[164:167], v[196:199], v[42:45]
	v_mfma_f32_16x16x32_bf16 v[30:33], v[156:159], v[204:207], v[30:33]
	v_mfma_f32_16x16x32_bf16 v[26:29], v[164:167], v[204:207], v[26:29]
	v_mfma_f32_16x16x32_bf16 v[14:17], v[156:159], v[212:215], v[14:17]
	v_mfma_f32_16x16x32_bf16 v[10:13], v[164:167], v[212:215], v[10:13]
	v_mfma_f32_16x16x32_bf16 v[62:65], v[160:163], v[192:195], v[62:65]
	v_mfma_f32_16x16x32_bf16 v[58:61], v[168:171], v[192:195], v[58:61]
	v_mfma_f32_16x16x32_bf16 v[46:49], v[160:163], v[200:203], v[46:49]
	v_mfma_f32_16x16x32_bf16 v[42:45], v[168:171], v[200:203], v[42:45]
	v_mfma_f32_16x16x32_bf16 v[30:33], v[160:163], v[208:211], v[30:33]
	v_mfma_f32_16x16x32_bf16 v[26:29], v[168:171], v[208:211], v[26:29]
	v_mfma_f32_16x16x32_bf16 v[14:17], v[160:163], v[216:219], v[14:17]
	v_mfma_f32_16x16x32_bf16 v[10:13], v[168:171], v[216:219], v[10:13]
	s_setprio 0
	s_setprio 1
	v_mfma_f32_16x16x32_bf16 v[54:57], v[172:175], v[188:191], v[54:57]
	v_mfma_f32_16x16x32_bf16 v[50:53], v[180:183], v[188:191], v[50:53]
	v_mfma_f32_16x16x32_bf16 v[38:41], v[172:175], v[196:199], v[38:41]
	v_mfma_f32_16x16x32_bf16 v[34:37], v[180:183], v[196:199], v[34:37]
	v_mfma_f32_16x16x32_bf16 v[22:25], v[172:175], v[204:207], v[22:25]
	v_mfma_f32_16x16x32_bf16 v[18:21], v[180:183], v[204:207], v[18:21]
	v_mfma_f32_16x16x32_bf16 v[6:9], v[172:175], v[212:215], v[6:9]
	v_mfma_f32_16x16x32_bf16 v[2:5], v[180:183], v[212:215], v[2:5]
	v_mfma_f32_16x16x32_bf16 v[54:57], v[176:179], v[192:195], v[54:57]
	v_mfma_f32_16x16x32_bf16 v[50:53], v[184:187], v[192:195], v[50:53]
	v_mfma_f32_16x16x32_bf16 v[38:41], v[176:179], v[200:203], v[38:41]
	v_mfma_f32_16x16x32_bf16 v[34:37], v[184:187], v[200:203], v[34:37]
	v_mfma_f32_16x16x32_bf16 v[22:25], v[176:179], v[208:211], v[22:25]
	v_mfma_f32_16x16x32_bf16 v[18:21], v[184:187], v[208:211], v[18:21]
	v_mfma_f32_16x16x32_bf16 v[6:9], v[176:179], v[216:219], v[6:9]
	v_mfma_f32_16x16x32_bf16 v[2:5], v[184:187], v[216:219], v[2:5]
	s_setprio 0
	s_barrier
	s_add_i32 s54, 0, 0x18000
	v_add_u32_e32 v155, s54, v153
	s_add_i32 s55, 0, 0x1c000
	ds_read_b128 v[156:159], v155
	ds_read_b128 v[160:163], v155 offset:1024
	ds_read_b128 v[164:167], v155 offset:2048
	ds_read_b128 v[168:171], v155 offset:3072
	v_add_u32_e32 v155, s55, v153
	ds_read_b128 v[172:175], v155
	ds_read_b128 v[176:179], v155 offset:1024
	ds_read_b128 v[180:183], v155 offset:2048
	ds_read_b128 v[184:187], v155 offset:3072
	s_add_u32 s98, s30, 0xb0000
	s_addc_u32 s99, s31, 0
	s_mov_b32 m0, s43
	ds_read_b128 v[188:191], v154 offset:32768
	ds_read_b128 v[192:195], v154 offset:33792
	ds_read_b128 v[196:199], v154 offset:34816
	ds_read_b128 v[200:203], v154 offset:35840
	ds_read_b128 v[204:207], v154 offset:36864
	ds_read_b128 v[208:211], v154 offset:37888
	ds_read_b128 v[212:215], v154 offset:38912
	ds_read_b128 v[216:219], v154 offset:39936
	global_load_lds_dwordx4 v130, s[98:99]
	s_mov_b32 m0, s44
	s_nop 0
	global_load_lds_dwordx4 v134, s[98:99]
	s_waitcnt vmcnt(8)
	s_waitcnt lgkmcnt(0)
	s_barrier
	s_setprio 1
	s_waitcnt lgkmcnt(0)
	v_mfma_f32_16x16x32_bf16 v[126:129], v[156:159], v[188:191], v[126:129]
	v_mfma_f32_16x16x32_bf16 v[122:125], v[164:167], v[188:191], v[122:125]
	v_mfma_f32_16x16x32_bf16 v[110:113], v[156:159], v[196:199], v[110:113]
	v_mfma_f32_16x16x32_bf16 v[106:109], v[164:167], v[196:199], v[106:109]
	v_mfma_f32_16x16x32_bf16 v[94:97], v[156:159], v[204:207], v[94:97]
	v_mfma_f32_16x16x32_bf16 v[90:93], v[164:167], v[204:207], v[90:93]
	v_mfma_f32_16x16x32_bf16 v[78:81], v[156:159], v[212:215], v[78:81]
	v_mfma_f32_16x16x32_bf16 v[74:77], v[164:167], v[212:215], v[74:77]
	v_mfma_f32_16x16x32_bf16 v[126:129], v[160:163], v[192:195], v[126:129]
	v_mfma_f32_16x16x32_bf16 v[122:125], v[168:171], v[192:195], v[122:125]
	v_mfma_f32_16x16x32_bf16 v[110:113], v[160:163], v[200:203], v[110:113]
	v_mfma_f32_16x16x32_bf16 v[106:109], v[168:171], v[200:203], v[106:109]
	v_mfma_f32_16x16x32_bf16 v[94:97], v[160:163], v[208:211], v[94:97]
	v_mfma_f32_16x16x32_bf16 v[90:93], v[168:171], v[208:211], v[90:93]
	v_mfma_f32_16x16x32_bf16 v[78:81], v[160:163], v[216:219], v[78:81]
	v_mfma_f32_16x16x32_bf16 v[74:77], v[168:171], v[216:219], v[74:77]
	s_setprio 0
	s_setprio 1
	v_mfma_f32_16x16x32_bf16 v[118:121], v[172:175], v[188:191], v[118:121]
	v_mfma_f32_16x16x32_bf16 v[114:117], v[180:183], v[188:191], v[114:117]
	v_mfma_f32_16x16x32_bf16 v[102:105], v[172:175], v[196:199], v[102:105]
	v_mfma_f32_16x16x32_bf16 v[98:101], v[180:183], v[196:199], v[98:101]
	v_mfma_f32_16x16x32_bf16 v[86:89], v[172:175], v[204:207], v[86:89]
	v_mfma_f32_16x16x32_bf16 v[82:85], v[180:183], v[204:207], v[82:85]
	v_mfma_f32_16x16x32_bf16 v[70:73], v[172:175], v[212:215], v[70:73]
	v_mfma_f32_16x16x32_bf16 v[66:69], v[180:183], v[212:215], v[66:69]
	v_mfma_f32_16x16x32_bf16 v[118:121], v[176:179], v[192:195], v[118:121]
	v_mfma_f32_16x16x32_bf16 v[114:117], v[184:187], v[192:195], v[114:117]
	v_mfma_f32_16x16x32_bf16 v[102:105], v[176:179], v[200:203], v[102:105]
	v_mfma_f32_16x16x32_bf16 v[98:101], v[184:187], v[200:203], v[98:101]
	v_mfma_f32_16x16x32_bf16 v[86:89], v[176:179], v[208:211], v[86:89]
	v_mfma_f32_16x16x32_bf16 v[82:85], v[184:187], v[208:211], v[82:85]
	v_mfma_f32_16x16x32_bf16 v[70:73], v[176:179], v[216:219], v[70:73]
	v_mfma_f32_16x16x32_bf16 v[66:69], v[184:187], v[216:219], v[66:69]
	s_setprio 0
	s_barrier
	s_add_i32 s98, s54, s35
	s_add_i32 m0, s98, 0xffffff80
	ds_read_b128 v[188:191], v154 offset:49152
	ds_read_b128 v[192:195], v154 offset:50176
	ds_read_b128 v[196:199], v154 offset:51200
	ds_read_b128 v[200:203], v154 offset:52224
	ds_read_b128 v[204:207], v154 offset:53248
	ds_read_b128 v[208:211], v154 offset:54272
	ds_read_b128 v[212:215], v154 offset:55296
	ds_read_b128 v[216:219], v154 offset:56320
	global_load_lds_dwordx4 v132, s[28:29] offset:128
	s_add_i32 m0, s98, 0x1f80
	s_add_i32 s98, s55, s35
	global_load_lds_dwordx4 v136, s[28:29] offset:128
	s_add_u32 s28, s28, 0xb0080
	s_addc_u32 s29, s29, 0
	s_mov_b32 m0, s98
	s_nop 0
	global_load_lds_dwordx4 v132, s[28:29]
	s_add_i32 m0, s98, 0x2000
	s_nop 0
	global_load_lds_dwordx4 v136, s[28:29]
	s_add_i32 m0, s46, 0xffffff80
	s_nop 0
	global_load_lds_dwordx4 v130, s[30:31] offset:128
	s_add_i32 m0, s47, 0xffffff80
	s_nop 0
	global_load_lds_dwordx4 v134, s[30:31] offset:128
	s_waitcnt vmcnt(8)
	s_waitcnt lgkmcnt(0)
	s_barrier
	s_setprio 1
	s_waitcnt lgkmcnt(0)
	v_mfma_f32_16x16x32_bf16 v[62:65], v[156:159], v[188:191], v[62:65]
	v_mfma_f32_16x16x32_bf16 v[58:61], v[164:167], v[188:191], v[58:61]
	v_mfma_f32_16x16x32_bf16 v[46:49], v[156:159], v[196:199], v[46:49]
	v_mfma_f32_16x16x32_bf16 v[42:45], v[164:167], v[196:199], v[42:45]
	v_mfma_f32_16x16x32_bf16 v[30:33], v[156:159], v[204:207], v[30:33]
	v_mfma_f32_16x16x32_bf16 v[26:29], v[164:167], v[204:207], v[26:29]
	v_mfma_f32_16x16x32_bf16 v[14:17], v[156:159], v[212:215], v[14:17]
	v_mfma_f32_16x16x32_bf16 v[10:13], v[164:167], v[212:215], v[10:13]
	v_mfma_f32_16x16x32_bf16 v[62:65], v[160:163], v[192:195], v[62:65]
	v_mfma_f32_16x16x32_bf16 v[58:61], v[168:171], v[192:195], v[58:61]
	v_mfma_f32_16x16x32_bf16 v[46:49], v[160:163], v[200:203], v[46:49]
	v_mfma_f32_16x16x32_bf16 v[42:45], v[168:171], v[200:203], v[42:45]
	v_mfma_f32_16x16x32_bf16 v[30:33], v[160:163], v[208:211], v[30:33]
	v_mfma_f32_16x16x32_bf16 v[26:29], v[168:171], v[208:211], v[26:29]
	v_mfma_f32_16x16x32_bf16 v[14:17], v[160:163], v[216:219], v[14:17]
	v_mfma_f32_16x16x32_bf16 v[10:13], v[168:171], v[216:219], v[10:13]
	s_setprio 0
	s_setprio 1
	v_mfma_f32_16x16x32_bf16 v[54:57], v[172:175], v[188:191], v[54:57]
	v_mfma_f32_16x16x32_bf16 v[50:53], v[180:183], v[188:191], v[50:53]
	v_mfma_f32_16x16x32_bf16 v[38:41], v[172:175], v[196:199], v[38:41]
	v_mfma_f32_16x16x32_bf16 v[34:37], v[180:183], v[196:199], v[34:37]
	v_mfma_f32_16x16x32_bf16 v[22:25], v[172:175], v[204:207], v[22:25]
	v_mfma_f32_16x16x32_bf16 v[18:21], v[180:183], v[204:207], v[18:21]
	v_mfma_f32_16x16x32_bf16 v[6:9], v[172:175], v[212:215], v[6:9]
	v_mfma_f32_16x16x32_bf16 v[2:5], v[180:183], v[212:215], v[2:5]
	v_mfma_f32_16x16x32_bf16 v[54:57], v[176:179], v[192:195], v[54:57]
	v_mfma_f32_16x16x32_bf16 v[50:53], v[184:187], v[192:195], v[50:53]
	v_mfma_f32_16x16x32_bf16 v[38:41], v[176:179], v[200:203], v[38:41]
	v_mfma_f32_16x16x32_bf16 v[34:37], v[184:187], v[200:203], v[34:37]
	v_mfma_f32_16x16x32_bf16 v[22:25], v[176:179], v[208:211], v[22:25]
	v_mfma_f32_16x16x32_bf16 v[18:21], v[184:187], v[208:211], v[18:21]
	v_mfma_f32_16x16x32_bf16 v[6:9], v[176:179], v[216:219], v[6:9]
	v_mfma_f32_16x16x32_bf16 v[2:5], v[184:187], v[216:219], v[2:5]
	s_setprio 0
	s_barrier
	s_add_i32 s53, s53, 2
	s_add_u32 s20, s20, 0x100
	s_addc_u32 s21, s21, 0
	s_cmp_gt_u32 s53, 41
	s_cbranch_scc0 .LBB0_2031
	s_add_u32 s20, s17, 0xffffff00
	s_addc_u32 s21, s52, -1
	s_and_b64 vcc, exec, s[4:5]
	s_cbranch_vccnz .LBB0_2034
	v_mov_b32_e32 v2, 0
	v_mov_b32_e32 v3, 0
	v_mov_b64_e32 v[4:5], v[2:3]
	v_mov_b64_e32 v[6:7], v[2:3]
	v_mov_b64_e32 v[8:9], v[2:3]
	v_mov_b64_e32 v[10:11], v[2:3]
	v_mov_b64_e32 v[12:13], v[2:3]
	v_mov_b64_e32 v[14:15], v[2:3]
	v_mov_b64_e32 v[16:17], v[2:3]
	v_mov_b64_e32 v[18:19], v[2:3]
	v_mov_b64_e32 v[20:21], v[2:3]
	v_mov_b64_e32 v[22:23], v[2:3]
	v_mov_b64_e32 v[24:25], v[2:3]
	v_mov_b64_e32 v[26:27], v[2:3]
	v_mov_b64_e32 v[28:29], v[2:3]
	v_mov_b64_e32 v[30:31], v[2:3]
	v_mov_b64_e32 v[32:33], v[2:3]
	v_mov_b64_e32 v[34:35], v[2:3]
	v_mov_b64_e32 v[36:37], v[2:3]
	v_mov_b64_e32 v[38:39], v[2:3]
	v_mov_b64_e32 v[40:41], v[2:3]
	v_mov_b64_e32 v[42:43], v[2:3]
	v_mov_b64_e32 v[44:45], v[2:3]
	v_mov_b64_e32 v[46:47], v[2:3]
	v_mov_b64_e32 v[48:49], v[2:3]
	v_mov_b64_e32 v[50:51], v[2:3]
	v_mov_b64_e32 v[52:53], v[2:3]
	v_mov_b64_e32 v[54:55], v[2:3]
	v_mov_b64_e32 v[56:57], v[2:3]
	v_mov_b64_e32 v[58:59], v[2:3]
	v_mov_b64_e32 v[60:61], v[2:3]
	v_mov_b64_e32 v[62:63], v[2:3]
	v_mov_b64_e32 v[64:65], v[2:3]
	v_mov_b64_e32 v[66:67], v[2:3]
	v_mov_b64_e32 v[68:69], v[2:3]
	v_mov_b64_e32 v[70:71], v[2:3]
	v_mov_b64_e32 v[72:73], v[2:3]
	v_mov_b64_e32 v[74:75], v[2:3]
	v_mov_b64_e32 v[76:77], v[2:3]
	v_mov_b64_e32 v[78:79], v[2:3]
	v_mov_b64_e32 v[80:81], v[2:3]
	v_mov_b64_e32 v[82:83], v[2:3]
	v_mov_b64_e32 v[84:85], v[2:3]
	v_mov_b64_e32 v[86:87], v[2:3]
	v_mov_b64_e32 v[88:89], v[2:3]
	v_mov_b64_e32 v[90:91], v[2:3]
	v_mov_b64_e32 v[92:93], v[2:3]
	v_mov_b64_e32 v[94:95], v[2:3]
	v_mov_b64_e32 v[96:97], v[2:3]
	v_mov_b64_e32 v[98:99], v[2:3]
	v_mov_b64_e32 v[100:101], v[2:3]
	v_mov_b64_e32 v[102:103], v[2:3]
	v_mov_b64_e32 v[104:105], v[2:3]
	v_mov_b64_e32 v[106:107], v[2:3]
	v_mov_b64_e32 v[108:109], v[2:3]
	v_mov_b64_e32 v[110:111], v[2:3]
	v_mov_b64_e32 v[112:113], v[2:3]
	v_mov_b64_e32 v[114:115], v[2:3]
	v_mov_b64_e32 v[116:117], v[2:3]
	v_mov_b64_e32 v[118:119], v[2:3]
	v_mov_b64_e32 v[120:121], v[2:3]
	v_mov_b64_e32 v[122:123], v[2:3]
	v_mov_b64_e32 v[124:125], v[2:3]
	v_mov_b64_e32 v[126:127], v[2:3]
	v_mov_b64_e32 v[128:129], v[2:3]
	s_mov_b32 s10, s50
	s_mov_b32 s23, s51
	s_mov_b64 s[12:13], s[18:19]
	s_mov_b32 s45, s16
	s_andn2_b64 vcc, exec, s[2:3]
	s_cbranch_vccnz .LBB0_2035
	s_branch .LBB0_2036

.LBB0_2204:
	v_lshlrev_b32_e32 v14, 6, v0
	v_lshlrev_b32_e32 v16, 2, v0
	v_and_b32_e32 v139, 48, v0
	v_and_b32_e32 v14, 0x3c0, v14
	v_and_b32_e32 v151, 32, v16
	s_lshl_b32 s4, s4, 12
	v_bitop3_b32 v150, v14, v151, v139 bitop3:0x36
	s_and_b32 s4, s4, 0x3000
	v_or_b32_e32 v15, v14, v139
	v_or_b32_e32 v14, s4, v150
	s_lshl_b32 s4, s5, 13
	v_bitop3_b32 v15, s4, v15, v151 bitop3:0xf6
	s_mov_b64 s[4:5], 0x80
	s_add_i32 m0, s31, 0x18000
	v_lshl_add_u64 v[8:9], v[8:9], 0, s[4:5]
	s_waitcnt vmcnt(2)
	s_barrier
	global_load_lds_dwordx4 v[8:9], off
	v_lshl_add_u64 v[6:7], v[6:7], 0, s[4:5]
	s_add_i32 m0, s31, 0x1a000
	s_add_i32 s43, s31, 0x8000
	s_add_i32 s44, s31, 0xa000
	global_load_lds_dwordx4 v[6:7], off
	v_lshl_add_u64 v[4:5], v[4:5], 0, s[4:5]
	s_mov_b32 m0, s43
	s_add_u32 s24, s0, 0xb0080
	global_load_lds_dwordx4 v[4:5], off
	v_lshl_add_u64 v[2:3], v[2:3], 0, s[4:5]
	s_mov_b32 m0, s44
	s_addc_u32 s25, s1, 0
	global_load_lds_dwordx4 v[2:3], off
	s_add_i32 m0, s31, 0x1c000
	v_lshl_add_u64 v[2:3], s[24:25], 0, v[132:133]
	global_load_lds_dwordx4 v[2:3], off
	v_lshl_add_u64 v[2:3], s[24:25], 0, v[136:137]
	s_add_i32 m0, s31, 0x1e000
	s_add_u32 s45, s18, 0x5600100
	global_load_lds_dwordx4 v[2:3], off
	v_add_u16_e32 v2, v10, v11
	s_addc_u32 s46, s19, 0
	v_lshrrev_b16_e32 v4, 1, v2
	v_add_lshl_u32 v142, v12, v4, 1
	v_mov_b32_e32 v143, v133
	s_add_u32 s47, s22, 0x2b80100
	s_waitcnt vmcnt(6)
	v_lshl_add_u64 v[2:3], s[18:19], 0, v[142:143]
	s_mov_b64 s[24:25], 0x56b0080
	v_add_lshl_u32 v144, v13, v4, 1
	v_mov_b32_e32 v145, v133
	s_addc_u32 s48, s21, 0
	s_add_i32 s22, 0, 0x10000
	s_add_i32 s23, 0, 0x14000
	s_add_i32 s28, 0, 0x18000
	s_add_i32 s29, 0, 0x1c000
	v_lshl_add_u64 v[146:147], v[2:3], 0, s[24:25]
	v_lshl_add_u64 v[2:3], s[18:19], 0, v[144:145]
	s_add_i32 s52, s22, s20
	s_add_i32 s54, s23, s20
	s_add_i32 s56, s28, s20
	s_add_i32 s58, s29, s20
	v_lshl_add_u64 v[148:149], v[2:3], 0, s[24:25]
	s_mov_b32 s49, -2
	v_add_u32_e32 v152, s22, v14
	v_add_u32_e32 v153, s23, v14
	v_add_u32_e32 v154, 0, v15
	s_add_i32 s50, s31, 0xc000
	s_add_i32 s51, s31, 0xe000
	s_add_i32 s53, s52, 0x2000
	s_add_i32 s55, s54, 0x2000
	v_add_u32_e32 v155, s28, v14
	v_add_u32_e32 v156, s29, v14
	s_add_i32 s57, s56, 0x2000
	s_add_i32 s59, s58, 0x2000
	s_mov_b64 s[18:19], 0x100
	v_mov_b32_e32 v2, v133
	v_mov_b32_e32 v3, v133
	v_mov_b64_e32 v[4:5], v[2:3]
	v_mov_b64_e32 v[6:7], v[2:3]
	v_mov_b64_e32 v[8:9], v[2:3]
	v_mov_b64_e32 v[10:11], v[2:3]
	v_mov_b64_e32 v[12:13], v[2:3]
	v_mov_b64_e32 v[14:15], v[2:3]
	v_mov_b64_e32 v[16:17], v[2:3]
	v_mov_b64_e32 v[18:19], v[2:3]
	v_mov_b64_e32 v[20:21], v[2:3]
	v_mov_b64_e32 v[22:23], v[2:3]
	v_mov_b64_e32 v[24:25], v[2:3]
	v_mov_b64_e32 v[26:27], v[2:3]
	v_mov_b64_e32 v[28:29], v[2:3]
	v_mov_b64_e32 v[30:31], v[2:3]
	v_mov_b64_e32 v[32:33], v[2:3]
	v_mov_b64_e32 v[34:35], v[2:3]
	v_mov_b64_e32 v[36:37], v[2:3]
	v_mov_b64_e32 v[38:39], v[2:3]
	v_mov_b64_e32 v[40:41], v[2:3]
	v_mov_b64_e32 v[42:43], v[2:3]
	v_mov_b64_e32 v[44:45], v[2:3]
	v_mov_b64_e32 v[46:47], v[2:3]
	v_mov_b64_e32 v[48:49], v[2:3]
	v_mov_b64_e32 v[50:51], v[2:3]
	v_mov_b64_e32 v[52:53], v[2:3]
	v_mov_b64_e32 v[54:55], v[2:3]
	v_mov_b64_e32 v[56:57], v[2:3]
	v_mov_b64_e32 v[58:59], v[2:3]
	v_mov_b64_e32 v[60:61], v[2:3]
	v_mov_b64_e32 v[62:63], v[2:3]
	v_mov_b64_e32 v[64:65], v[2:3]
	v_mov_b64_e32 v[66:67], v[2:3]
	v_mov_b64_e32 v[68:69], v[2:3]
	v_mov_b64_e32 v[70:71], v[2:3]
	v_mov_b64_e32 v[72:73], v[2:3]
	v_mov_b64_e32 v[74:75], v[2:3]
	v_mov_b64_e32 v[76:77], v[2:3]
	v_mov_b64_e32 v[78:79], v[2:3]
	v_mov_b64_e32 v[80:81], v[2:3]
	v_mov_b64_e32 v[82:83], v[2:3]
	v_mov_b64_e32 v[84:85], v[2:3]
	v_mov_b64_e32 v[86:87], v[2:3]
	v_mov_b64_e32 v[88:89], v[2:3]
	v_mov_b64_e32 v[90:91], v[2:3]
	v_mov_b64_e32 v[92:93], v[2:3]
	v_mov_b64_e32 v[94:95], v[2:3]
	v_mov_b64_e32 v[96:97], v[2:3]
	v_mov_b64_e32 v[98:99], v[2:3]
	v_mov_b64_e32 v[100:101], v[2:3]
	v_mov_b64_e32 v[102:103], v[2:3]
	v_mov_b64_e32 v[104:105], v[2:3]
	v_mov_b64_e32 v[106:107], v[2:3]
	v_mov_b64_e32 v[108:109], v[2:3]
	v_mov_b64_e32 v[110:111], v[2:3]
	v_mov_b64_e32 v[112:113], v[2:3]
	v_mov_b64_e32 v[114:115], v[2:3]
	v_mov_b64_e32 v[116:117], v[2:3]
	v_mov_b64_e32 v[118:119], v[2:3]
	v_mov_b64_e32 v[120:121], v[2:3]
	v_mov_b64_e32 v[122:123], v[2:3]
	v_mov_b64_e32 v[124:125], v[2:3]
	v_mov_b64_e32 v[126:127], v[2:3]
	v_mov_b64_e32 v[128:129], v[2:3]
	s_waitcnt vmcnt(0)
	s_barrier

.LBB0_2213:
	s_lshl_b32 s17, s17, 12
	s_and_b32 s17, s17, 0x3000
	v_or_b32_e32 v10, s17, v150
	v_lshl_or_b32 v11, s16, 13, v150
	s_mov_b64 s[16:17], 0x80
	s_add_i32 m0, s31, 0x18000
	v_lshl_add_u64 v[2:3], v[2:3], 0, s[16:17]
	s_waitcnt vmcnt(2)
	s_barrier
	global_load_lds_dwordx4 v[2:3], off
	v_lshl_add_u64 v[2:3], v[4:5], 0, s[16:17]
	s_add_i32 m0, s31, 0x1a000
	s_add_i32 s38, s31, 0x8000
	s_add_i32 s39, s31, 0xa000
	global_load_lds_dwordx4 v[2:3], off
	v_lshl_add_u64 v[2:3], v[8:9], 0, s[16:17]
	s_mov_b32 m0, s38
	s_add_u32 s20, s0, 0xb0080
	global_load_lds_dwordx4 v[2:3], off
	v_lshl_add_u64 v[2:3], v[6:7], 0, s[16:17]
	s_mov_b32 m0, s39
	s_addc_u32 s21, s1, 0
	global_load_lds_dwordx4 v[2:3], off
	s_add_i32 m0, s31, 0x1c000
	v_lshl_add_u64 v[2:3], s[20:21], 0, v[132:133]
	global_load_lds_dwordx4 v[2:3], off
	v_lshl_add_u64 v[2:3], s[20:21], 0, v[136:137]
	s_add_i32 m0, s31, 0x1e000
	s_add_u32 s40, s14, 0x5600100
	global_load_lds_dwordx4 v[2:3], off
	s_addc_u32 s42, s15, 0
	v_lshl_add_u64 v[2:3], s[14:15], 0, v[142:143]
	s_mov_b64 s[20:21], 0x56b0080
	s_waitcnt vmcnt(6)
	v_lshl_add_u64 v[140:141], v[2:3], 0, s[20:21]
	v_lshl_add_u64 v[2:3], s[14:15], 0, v[144:145]
	s_add_u32 s43, s41, 0x2b80100
	v_lshl_add_u64 v[142:143], v[2:3], 0, s[20:21]
	s_addc_u32 s44, s11, 0
	v_mov_b32_e32 v2, 0
	s_add_i32 s48, s22, s18
	s_add_i32 s50, s23, s18
	s_add_i32 s52, s28, s18
	s_add_i32 s54, s29, s18
	s_mov_b32 s2, s13
	s_mov_b32 s45, -2
	v_add_u32_e32 v144, s22, v10
	v_add_u32_e32 v145, s23, v10
	v_add_u32_e32 v146, 0, v11
	s_add_i32 s46, s31, 0xc000
	s_add_i32 s47, s31, 0xe000
	s_add_i32 s49, s48, 0x2000
	s_add_i32 s51, s50, 0x2000
	v_add_u32_e32 v147, s28, v10
	v_add_u32_e32 v148, s29, v10
	s_add_i32 s53, s52, 0x2000
	s_add_i32 s55, s54, 0x2000
	s_mov_b64 s[18:19], 0x100
	v_mov_b32_e32 v4, v2
	v_mov_b32_e32 v5, v2
	v_mov_b64_e32 v[6:7], v[4:5]
	v_mov_b64_e32 v[8:9], v[4:5]
	v_mov_b64_e32 v[10:11], v[4:5]
	v_mov_b64_e32 v[12:13], v[4:5]
	v_mov_b64_e32 v[14:15], v[4:5]
	v_mov_b64_e32 v[16:17], v[4:5]
	v_mov_b64_e32 v[18:19], v[4:5]
	v_mov_b64_e32 v[20:21], v[4:5]
	v_mov_b64_e32 v[22:23], v[4:5]
	v_mov_b64_e32 v[24:25], v[4:5]
	v_mov_b64_e32 v[26:27], v[4:5]
	v_mov_b64_e32 v[28:29], v[4:5]
	v_mov_b64_e32 v[30:31], v[4:5]
	v_mov_b64_e32 v[32:33], v[4:5]
	v_mov_b64_e32 v[34:35], v[4:5]
	v_mov_b64_e32 v[36:37], v[4:5]
	v_mov_b64_e32 v[38:39], v[4:5]
	v_mov_b64_e32 v[40:41], v[4:5]
	v_mov_b64_e32 v[42:43], v[4:5]
	v_mov_b64_e32 v[44:45], v[4:5]
	v_mov_b64_e32 v[46:47], v[4:5]
	v_mov_b64_e32 v[48:49], v[4:5]
	v_mov_b64_e32 v[50:51], v[4:5]
	v_mov_b64_e32 v[52:53], v[4:5]
	v_mov_b64_e32 v[54:55], v[4:5]
	v_mov_b64_e32 v[56:57], v[4:5]
	v_mov_b64_e32 v[58:59], v[4:5]
	v_mov_b64_e32 v[60:61], v[4:5]
	v_mov_b64_e32 v[62:63], v[4:5]
	v_mov_b64_e32 v[64:65], v[4:5]
	v_mov_b64_e32 v[66:67], v[4:5]
	v_mov_b64_e32 v[68:69], v[4:5]
	v_mov_b64_e32 v[70:71], v[4:5]
	v_mov_b64_e32 v[72:73], v[4:5]
	v_mov_b64_e32 v[74:75], v[4:5]
	v_mov_b64_e32 v[76:77], v[4:5]
	v_mov_b64_e32 v[78:79], v[4:5]
	v_mov_b64_e32 v[80:81], v[4:5]
	v_mov_b64_e32 v[82:83], v[4:5]
	v_mov_b64_e32 v[84:85], v[4:5]
	v_mov_b64_e32 v[86:87], v[4:5]
	v_mov_b64_e32 v[88:89], v[4:5]
	v_mov_b64_e32 v[90:91], v[4:5]
	v_mov_b64_e32 v[92:93], v[4:5]
	v_mov_b64_e32 v[94:95], v[4:5]
	v_mov_b64_e32 v[96:97], v[4:5]
	v_mov_b64_e32 v[98:99], v[4:5]
	v_mov_b64_e32 v[100:101], v[4:5]
	v_mov_b64_e32 v[102:103], v[4:5]
	v_mov_b64_e32 v[104:105], v[4:5]
	v_mov_b64_e32 v[106:107], v[4:5]
	v_mov_b64_e32 v[108:109], v[4:5]
	v_mov_b64_e32 v[110:111], v[4:5]
	v_mov_b64_e32 v[112:113], v[4:5]
	v_mov_b64_e32 v[114:115], v[4:5]
	v_mov_b64_e32 v[116:117], v[4:5]
	v_mov_b64_e32 v[118:119], v[4:5]
	v_mov_b64_e32 v[120:121], v[4:5]
	v_mov_b64_e32 v[122:123], v[4:5]
	v_mov_b64_e32 v[124:125], v[4:5]
	v_mov_b64_e32 v[126:127], v[4:5]
	v_mov_b64_e32 v[128:129], v[4:5]
	v_mov_b32_e32 v3, v4
	s_barrier
